# norm<1>: rewritten pass 2/3 with 16-byte row stores (adjacent lanes exchange 8-byte pieces by DPP)
# baseline (speedup 1.0000x reference)
; #define LAS __attribute__((address_space(3)))
; template <int MODE> ...
;     ...
;     __syncthreads();
; #pragma unroll
;     for (int i = 0; i < 2; ++i) { const int o = 4 * (tid + NTHREADS * i);
;         if (MODE != 0) { *(LAS f32x4*)(GP + o) = *(const f32x4*)(gpost + o); const f32x4 g = *(const f32x4*)(gprev + o); *(LAS f32x4*)(GI + o) = (f32x4){1.f / g.x, 1.f / g.y, 1.f / g.z, 1.f / g.w}; }
;         if (MODE != 2) *(LAS f32x4*)(GN + o) = *(const f32x4*)(gpre + o); }
;     __syncthreads();
;     const int lo4 = 4 * lane;
; #pragma unroll 1
;     for (int row = gw; row < SEQ; row += NGW) {
.LBB0_772:
	s_cmp_gt_i32 s36, 6
	s_cselect_b64 s[6:7], -1, 0
	s_xor_b64 s[4:5], s[4:5], -1
	s_or_b64 s[4:5], s[6:7], s[4:5]
	s_and_b64 vcc, exec, s[4:5]
	s_cbranch_vccnz .LBB0_778
	s_mov_b64 s[12:13], 0
	v_mbcnt_lo_u32_b32 v2, -1, 0
	v_mbcnt_hi_u32_b32 v2, -1, v2
	s_load_dwordx4 s[4:7], s[0:1], 0x10
	s_load_dwordx2 s[8:9], s[0:1], 0x70
	v_lshlrev_b32_e32 v0, 2, v2
	v_lshl_add_u32 v24, s89, 8, v0
	v_ashrrev_i32_e32 v25, 31, v24
	v_lshlrev_b64 v[12:13], 2, v[24:25]
	v_add_u32_e32 v16, 0x800, v24
	s_waitcnt lgkmcnt(0)
	v_lshl_add_u64 v[8:9], s[4:5], 0, v[12:13]
	v_ashrrev_i32_e32 v17, 31, v16
	s_waitcnt vmcnt(0)
	s_barrier
	v_lshl_add_u64 v[4:5], s[6:7], 0, v[12:13]
	global_load_dwordx4 v[8:11], v[8:9], off
	v_lshl_add_u64 v[12:13], s[8:9], 0, v[12:13]
	v_lshlrev_b64 v[26:27], 2, v[16:17]
	global_load_dwordx4 v[4:7], v[4:5], off
	v_lshl_add_u64 v[16:17], s[6:7], 0, v[26:27]
	global_load_dwordx4 v[12:15], v[12:13], off
	v_lshl_add_u64 v[20:21], s[4:5], 0, v[26:27]
	global_load_dwordx4 v[16:19], v[16:17], off
	v_lshl_add_u32 v1, v24, 2, 0
	global_load_dwordx4 v[20:23], v[20:21], off
	v_lshl_add_u64 v[24:25], s[8:9], 0, v[26:27]
	global_load_dwordx4 v[24:27], v[24:25], off
	s_cmpk_gt_i32 s40, 0x1fff
	s_waitcnt vmcnt(5)
	v_div_scale_f32 v3, s[4:5], v8, v8, 1.0
	v_div_scale_f32 v29, s[8:9], v11, v11, 1.0
	s_waitcnt vmcnt(4)
	ds_write_b128 v1, v[4:7]
	v_div_scale_f32 v5, s[4:5], v9, v9, 1.0
	s_waitcnt vmcnt(3)
	ds_write_b128 v1, v[12:15] offset:16384
	v_rcp_f32_e32 v12, v3
	v_div_scale_f32 v7, s[6:7], v10, v10, 1.0
	v_rcp_f32_e32 v13, v5
	s_waitcnt vmcnt(2)
	ds_write_b128 v1, v[16:19] offset:8192
	s_waitcnt vmcnt(1)
	v_div_scale_f32 v16, s[10:11], v20, v20, 1.0
	v_rcp_f32_e32 v14, v7
	v_rcp_f32_e32 v19, v16
	v_rcp_f32_e32 v15, v29
	v_fma_f32 v32, -v3, v12, 1.0
	v_div_scale_f32 v4, vcc, 1.0, v8, 1.0
	v_fma_f32 v33, -v5, v13, 1.0
	v_fmac_f32_e32 v12, v32, v12
	v_div_scale_f32 v6, s[4:5], 1.0, v9, 1.0
	v_fma_f32 v34, -v7, v14, 1.0
	v_fmac_f32_e32 v13, v33, v13
	v_fma_f32 v32, -v16, v19, 1.0
	v_mul_f32_e32 v33, v4, v12
	v_div_scale_f32 v28, s[6:7], 1.0, v10, 1.0
	v_fma_f32 v35, -v29, v15, 1.0
	v_fmac_f32_e32 v14, v34, v14
	v_mul_f32_e32 v34, v6, v13
	v_fmac_f32_e32 v19, v32, v19
	v_fma_f32 v32, -v3, v33, v4
	v_div_scale_f32 v30, s[8:9], 1.0, v11, 1.0
	v_fmac_f32_e32 v15, v35, v15
	v_mul_f32_e32 v35, v28, v14
	v_fma_f32 v37, -v5, v34, v6
	v_fmac_f32_e32 v33, v32, v12
	v_div_scale_f32 v17, s[10:11], 1.0, v20, 1.0
	v_mul_f32_e32 v36, v30, v15
	v_fma_f32 v38, -v7, v35, v28
	v_fmac_f32_e32 v34, v37, v13
	v_fma_f32 v3, -v3, v33, v4
	v_div_scale_f32 v18, s[14:15], v21, v21, 1.0
	v_fma_f32 v39, -v29, v36, v30
	v_mul_f32_e32 v40, v17, v19
	v_fmac_f32_e32 v35, v38, v14
	v_fma_f32 v5, -v5, v34, v6
	v_div_fmas_f32 v3, v3, v12, v33
	s_mov_b64 vcc, s[4:5]
	v_rcp_f32_e32 v31, v18
	v_fmac_f32_e32 v36, v39, v15
	v_fma_f32 v32, -v16, v40, v17
	v_fma_f32 v6, -v7, v35, v28
	v_div_fixup_f32 v4, v3, v8, 1.0
	v_div_fmas_f32 v3, v5, v13, v34
	s_mov_b64 vcc, s[6:7]
	v_fma_f32 v7, -v29, v36, v30
	v_fmac_f32_e32 v40, v32, v19
	v_div_fixup_f32 v5, v3, v9, 1.0
	v_div_fmas_f32 v3, v6, v14, v35
	s_mov_b64 vcc, s[8:9]
	v_fma_f32 v12, -v16, v40, v17
	v_div_fixup_f32 v6, v3, v10, 1.0
	v_div_fmas_f32 v3, v7, v15, v36
	s_mov_b64 vcc, s[10:11]
	v_div_fixup_f32 v7, v3, v11, 1.0
	v_div_fmas_f32 v3, v12, v19, v40
	ds_write_b128 v1, v[4:7] offset:32768
	v_div_fixup_f32 v4, v3, v20, 1.0
	v_fma_f32 v3, -v18, v31, 1.0
	v_fmac_f32_e32 v31, v3, v31
	v_div_scale_f32 v3, vcc, 1.0, v21, 1.0
	v_mul_f32_e32 v5, v3, v31
	v_fma_f32 v6, -v18, v5, v3
	v_fmac_f32_e32 v5, v6, v31
	v_div_scale_f32 v6, s[4:5], v22, v22, 1.0
	v_rcp_f32_e32 v7, v6
	v_fma_f32 v3, -v18, v5, v3
	v_div_fmas_f32 v3, v3, v31, v5
	v_div_fixup_f32 v5, v3, v21, 1.0
	v_fma_f32 v3, -v6, v7, 1.0
	v_fmac_f32_e32 v7, v3, v7
	v_div_scale_f32 v3, vcc, 1.0, v22, 1.0
	v_mul_f32_e32 v8, v3, v7
	v_fma_f32 v9, -v6, v8, v3
	v_fmac_f32_e32 v8, v9, v7
	v_div_scale_f32 v9, s[4:5], v23, v23, 1.0
	v_rcp_f32_e32 v10, v9
	v_fma_f32 v3, -v6, v8, v3
	v_div_fmas_f32 v3, v3, v7, v8
	v_div_fixup_f32 v6, v3, v22, 1.0
	v_fma_f32 v3, -v9, v10, 1.0
	v_fmac_f32_e32 v10, v3, v10
	v_div_scale_f32 v3, vcc, 1.0, v23, 1.0
	v_mul_f32_e32 v7, v3, v10
	v_fma_f32 v8, -v9, v7, v3
	v_fmac_f32_e32 v7, v8, v10
	v_fma_f32 v3, -v9, v7, v3
	v_div_fmas_f32 v3, v3, v10, v7
	v_div_fixup_f32 v7, v3, v23, 1.0
	ds_write_b128 v1, v[4:7] offset:40960
	s_waitcnt vmcnt(0)
	ds_write_b128 v1, v[24:27] offset:24576
	s_waitcnt lgkmcnt(0)
	s_barrier
	s_cbranch_scc1 .LBB0_778
	s_load_dwordx2 s[6:7], s[0:1], 0xe8
	s_ashr_i32 s41, s40, 31
	s_lshl_b64 s[8:9], s[40:41], 2
	v_ashrrev_i32_e32 v1, 31, v0
	v_cmp_eq_u32_e64 s[4:5], 0, v2
	s_waitcnt lgkmcnt(0)
	s_add_u32 s8, s6, s8
	s_addc_u32 s9, s7, s9
	s_add_u32 s64, s8, 0x2c0000
	s_addc_u32 s65, s9, 0
	s_ashr_i32 s39, s38, 31
	s_lshl_b64 s[8:9], s[38:39], 2
	s_lshl_b64 s[10:11], s[40:41], 13
	s_add_u32 s6, s6, s10
	s_addc_u32 s7, s7, s11
	v_mbcnt_lo_u32_b32 v2, -1, 0
	v_lshl_add_u32 v71, v0, 2, 0
	v_lshl_add_u64 v[0:1], v[0:1], 1, s[6:7]
	s_lshl_b64 s[10:11], s[38:39], 13
	s_mov_b64 s[14:15], 0x3000000
	s_mov_b64 s[18:19], 0x3000200
	s_mov_b64 s[20:21], 0x3000400
	s_mov_b64 s[22:23], 0x3000600
	s_mov_b64 s[24:25], 0x3000800
	s_mov_b64 s[26:27], 0x3000a00
	s_mov_b64 s[42:43], 0x3000c00
	s_mov_b64 s[44:45], 0x3000e00
	s_mov_b64 s[46:47], 0x3001000
	s_mov_b32 s39, 0x3001000
	s_mov_b32 s41, 0x7001000
	s_mov_b64 s[48:49], 0x3001200
	s_mov_b64 s[50:51], 0x3001400
	s_mov_b64 s[52:53], 0x3001600
	s_mov_b64 s[54:55], 0x3001800
	s_mov_b64 s[56:57], 0x3001a00
	s_mov_b64 s[58:59], 0x3001c00
	s_mov_b64 s[60:61], 0x3001e00
	v_mov_b32_e32 v98, 0
	v_mov_b32_e32 v99, 0x358637bd
	s_mov_b32 s66, 0x800000
	v_mbcnt_hi_u32_b32 v100, -1, v2
	s_mov_b32 s67, s40
	s_mov_b32 s96, 0x3000000
	s_mov_b32 s97, 0x3001000
	s_mov_b32 s92, 0xaaaaaaaa
	s_mov_b32 s93, 0xaaaaaaaa
	s_branch .LBB0_776
; #define LAS __attribute__((address_space(3)))
; __device__ __forceinline__ unsigned pk2(float lo, float hi) { const f32x2c v = {lo, hi}; return __builtin_bit_cast(unsigned, __builtin_convertvector(v, bf16x2c)); }
; __device__ __forceinline__ float bflo(unsigned w) { return __uint_as_float(w << 16); }
; __device__ __forceinline__ float bfhi(unsigned w) { return __uint_as_float(w & 0xffff0000u); }
; #define LAUNDER_ROW(pw, hw) do { LAUNDER8(pw, 0); LAUNDER8(pw, 8); LAUNDER8(hw, 0); LAUNDER8(hw, 8); } while (0)
; template <int MODE> ...
;     ...
;                 LAUNDER_ROW(pw, hw);
;                 float ri2 = ri, rstdb = rstd; asm volatile("" : "+v"(ri2), "+v"(rstdb) :: "memory");
; #pragma unroll
;                 for (int j = 0; j < 16; ++j) { const f32x4 g = *(const LAS f32x4*)(GP + lo4 + 256 * j), gi = *(const LAS f32x4*)(GI + lo4 + 256 * j), gn = *(const LAS f32x4*)(GN + lo4 + 256 * j);
;                     f32x4 x;
;                     x.x = bflo(pw[j].x) * ri2 * gi.x + bflo(hw[j].x) * rstdb * g.x; x.y = bfhi(pw[j].x) * ri2 * gi.y + bfhi(hw[j].x) * rstdb * g.y;
;                     x.z = bflo(pw[j].y) * ri2 * gi.z + bflo(hw[j].y) * rstdb * g.z; x.w = bfhi(pw[j].y) * ri2 * gi.w + bfhi(hw[j].y) * rstdb * g.w;
;                     v2u w; w.x = pk2(x.x * rstd2 * gn.x, x.y * rstd2 * gn.y); w.y = pk2(x.z * rstd2 * gn.z, x.w * rstd2 * gn.w);
;                     *(v2u*)(pw_out + lo4 + 256 * j) = w;
;                     if (j & 1) __builtin_amdgcn_sched_barrier(0); }
.LBB0_775:
	s_or_b64 exec, exec, s[6:7]
	v_mov_b32_e32 v236, 0x1f8
	v_cndmask_b32_e64 v236, 0, v236, s[92:93]
	v_add_u32_e32 v237, s96, v236
	v_add_u32_e32 v238, s97, v236
	v_add_co_u32_e32 v224, vcc, v237, v66
	s_nop 1
	v_addc_co_u32_e32 v225, vcc, 0, v67, vcc
	v_add_co_u32_e32 v226, vcc, v238, v66
	s_nop 1
	v_addc_co_u32_e32 v227, vcc, 0, v67, vcc
	ds_read_b128 v[196:199], v71 offset:16384
	ds_read_b128 v[204:207], v71 offset:17408
	v_mul_f32_e32 v212, v70, v132
	v_mul_f32_e32 v213, v70, v133
	v_mul_f32_e32 v214, v70, v134
	v_mul_f32_e32 v215, v70, v135
	s_waitcnt lgkmcnt(1)
	v_mul_f32_e32 v212, v196, v212
	v_mul_f32_e32 v213, v197, v213
	v_mul_f32_e32 v214, v198, v214
	v_mul_f32_e32 v215, v199, v215
	v_cvt_pk_bf16_f32 v216, v212, v213
	v_cvt_pk_bf16_f32 v217, v214, v215
	ds_read_b128 v[196:199], v71 offset:18432
	v_mul_f32_e32 v212, v70, v136
	v_mul_f32_e32 v213, v70, v137
	v_mul_f32_e32 v214, v70, v138
	v_mul_f32_e32 v215, v70, v139
	s_waitcnt lgkmcnt(1)
	v_mul_f32_e32 v212, v204, v212
	v_mul_f32_e32 v213, v205, v213
	v_mul_f32_e32 v214, v206, v214
	v_mul_f32_e32 v215, v207, v215
	v_cvt_pk_bf16_f32 v218, v212, v213
	v_cvt_pk_bf16_f32 v219, v214, v215
	s_nop 1
	v_mov_b32_dpp v220, v216 quad_perm:[1,0,3,2] row_mask:0xf bank_mask:0xf
	v_mov_b32_dpp v221, v217 quad_perm:[1,0,3,2] row_mask:0xf bank_mask:0xf
	v_mov_b32_dpp v222, v218 quad_perm:[1,0,3,2] row_mask:0xf bank_mask:0xf
	v_mov_b32_dpp v223, v219 quad_perm:[1,0,3,2] row_mask:0xf bank_mask:0xf
	v_cndmask_b32_e64 v228, v216, v222, s[92:93]
	v_cndmask_b32_e64 v229, v217, v223, s[92:93]
	v_cndmask_b32_e64 v230, v220, v218, s[92:93]
	v_cndmask_b32_e64 v231, v221, v219, s[92:93]
	global_store_dwordx4 v[224:225], v[228:231], off
	ds_read_b128 v[204:207], v71 offset:19456
	v_mul_f32_e32 v212, v70, v140
	v_mul_f32_e32 v213, v70, v141
	v_mul_f32_e32 v214, v70, v142
	v_mul_f32_e32 v215, v70, v143
	s_waitcnt lgkmcnt(1)
	v_mul_f32_e32 v212, v196, v212
	v_mul_f32_e32 v213, v197, v213
	v_mul_f32_e32 v214, v198, v214
	v_mul_f32_e32 v215, v199, v215
	v_cvt_pk_bf16_f32 v216, v212, v213
	v_cvt_pk_bf16_f32 v217, v214, v215
	ds_read_b128 v[196:199], v71 offset:20480
	v_mul_f32_e32 v212, v70, v144
	v_mul_f32_e32 v213, v70, v145
	v_mul_f32_e32 v214, v70, v146
	v_mul_f32_e32 v215, v70, v147
	s_waitcnt lgkmcnt(1)
	v_mul_f32_e32 v212, v204, v212
	v_mul_f32_e32 v213, v205, v213
	v_mul_f32_e32 v214, v206, v214
	v_mul_f32_e32 v215, v207, v215
	v_cvt_pk_bf16_f32 v218, v212, v213
	v_cvt_pk_bf16_f32 v219, v214, v215
	s_nop 1
	v_mov_b32_dpp v220, v216 quad_perm:[1,0,3,2] row_mask:0xf bank_mask:0xf
	v_mov_b32_dpp v221, v217 quad_perm:[1,0,3,2] row_mask:0xf bank_mask:0xf
	v_mov_b32_dpp v222, v218 quad_perm:[1,0,3,2] row_mask:0xf bank_mask:0xf
	v_mov_b32_dpp v223, v219 quad_perm:[1,0,3,2] row_mask:0xf bank_mask:0xf
	v_cndmask_b32_e64 v232, v216, v222, s[92:93]
	v_cndmask_b32_e64 v233, v217, v223, s[92:93]
	v_cndmask_b32_e64 v234, v220, v218, s[92:93]
	v_cndmask_b32_e64 v235, v221, v219, s[92:93]
	global_store_dwordx4 v[224:225], v[232:235], off offset:1024
	ds_read_b128 v[204:207], v71 offset:21504
	v_mul_f32_e32 v212, v70, v148
	v_mul_f32_e32 v213, v70, v149
	v_mul_f32_e32 v214, v70, v150
	v_mul_f32_e32 v215, v70, v151
	s_waitcnt lgkmcnt(1)
	v_mul_f32_e32 v212, v196, v212
	v_mul_f32_e32 v213, v197, v213
	v_mul_f32_e32 v214, v198, v214
	v_mul_f32_e32 v215, v199, v215
	v_cvt_pk_bf16_f32 v216, v212, v213
	v_cvt_pk_bf16_f32 v217, v214, v215
	ds_read_b128 v[196:199], v71 offset:22528
	v_mul_f32_e32 v212, v70, v152
	v_mul_f32_e32 v213, v70, v153
	v_mul_f32_e32 v214, v70, v154
	v_mul_f32_e32 v215, v70, v155
	s_waitcnt lgkmcnt(1)
	v_mul_f32_e32 v212, v204, v212
	v_mul_f32_e32 v213, v205, v213
	v_mul_f32_e32 v214, v206, v214
	v_mul_f32_e32 v215, v207, v215
	v_cvt_pk_bf16_f32 v218, v212, v213
	v_cvt_pk_bf16_f32 v219, v214, v215
	s_nop 1
	v_mov_b32_dpp v220, v216 quad_perm:[1,0,3,2] row_mask:0xf bank_mask:0xf
	v_mov_b32_dpp v221, v217 quad_perm:[1,0,3,2] row_mask:0xf bank_mask:0xf
	v_mov_b32_dpp v222, v218 quad_perm:[1,0,3,2] row_mask:0xf bank_mask:0xf
	v_mov_b32_dpp v223, v219 quad_perm:[1,0,3,2] row_mask:0xf bank_mask:0xf
	v_cndmask_b32_e64 v228, v216, v222, s[92:93]
	v_cndmask_b32_e64 v229, v217, v223, s[92:93]
	v_cndmask_b32_e64 v230, v220, v218, s[92:93]
	v_cndmask_b32_e64 v231, v221, v219, s[92:93]
	global_store_dwordx4 v[224:225], v[228:231], off offset:2048
	ds_read_b128 v[204:207], v71 offset:23552
	v_mul_f32_e32 v212, v70, v156
	v_mul_f32_e32 v213, v70, v157
	v_mul_f32_e32 v214, v70, v158
	v_mul_f32_e32 v215, v70, v159
	s_waitcnt lgkmcnt(1)
	v_mul_f32_e32 v212, v196, v212
	v_mul_f32_e32 v213, v197, v213
	v_mul_f32_e32 v214, v198, v214
	v_mul_f32_e32 v215, v199, v215
	v_cvt_pk_bf16_f32 v216, v212, v213
	v_cvt_pk_bf16_f32 v217, v214, v215
	ds_read_b128 v[196:199], v71 offset:24576
	v_mul_f32_e32 v212, v70, v160
	v_mul_f32_e32 v213, v70, v161
	v_mul_f32_e32 v214, v70, v162
	v_mul_f32_e32 v215, v70, v163
	s_waitcnt lgkmcnt(1)
	v_mul_f32_e32 v212, v204, v212
	v_mul_f32_e32 v213, v205, v213
	v_mul_f32_e32 v214, v206, v214
	v_mul_f32_e32 v215, v207, v215
	v_cvt_pk_bf16_f32 v218, v212, v213
	v_cvt_pk_bf16_f32 v219, v214, v215
	s_nop 1
	v_mov_b32_dpp v220, v216 quad_perm:[1,0,3,2] row_mask:0xf bank_mask:0xf
	v_mov_b32_dpp v221, v217 quad_perm:[1,0,3,2] row_mask:0xf bank_mask:0xf
	v_mov_b32_dpp v222, v218 quad_perm:[1,0,3,2] row_mask:0xf bank_mask:0xf
	v_mov_b32_dpp v223, v219 quad_perm:[1,0,3,2] row_mask:0xf bank_mask:0xf
	v_cndmask_b32_e64 v232, v216, v222, s[92:93]
	v_cndmask_b32_e64 v233, v217, v223, s[92:93]
	v_cndmask_b32_e64 v234, v220, v218, s[92:93]
	v_cndmask_b32_e64 v235, v221, v219, s[92:93]
	global_store_dwordx4 v[224:225], v[232:235], off offset:3072
	ds_read_b128 v[204:207], v71 offset:25600
	v_mul_f32_e32 v212, v70, v164
	v_mul_f32_e32 v213, v70, v165
	v_mul_f32_e32 v214, v70, v166
	v_mul_f32_e32 v215, v70, v167
	s_waitcnt lgkmcnt(1)
; #define LAS __attribute__((address_space(3)))
; __device__ __forceinline__ unsigned pk2(float lo, float hi) { const f32x2c v = {lo, hi}; return __builtin_bit_cast(unsigned, __builtin_convertvector(v, bf16x2c)); }
; __device__ __forceinline__ float bflo(unsigned w) { return __uint_as_float(w << 16); }
; __device__ __forceinline__ float bfhi(unsigned w) { return __uint_as_float(w & 0xffff0000u); }
; #define LAUNDER_ROW(pw, hw) do { LAUNDER8(pw, 0); LAUNDER8(pw, 8); LAUNDER8(hw, 0); LAUNDER8(hw, 8); } while (0)
; template <int MODE> ...
;     ...
;                 LAUNDER_ROW(pw, hw);
;                 float ri2 = ri, rstdb = rstd; asm volatile("" : "+v"(ri2), "+v"(rstdb) :: "memory");
; #pragma unroll
;                 for (int j = 0; j < 16; ++j) { const f32x4 g = *(const LAS f32x4*)(GP + lo4 + 256 * j), gi = *(const LAS f32x4*)(GI + lo4 + 256 * j), gn = *(const LAS f32x4*)(GN + lo4 + 256 * j);
;                     f32x4 x;
;                     x.x = bflo(pw[j].x) * ri2 * gi.x + bflo(hw[j].x) * rstdb * g.x; x.y = bfhi(pw[j].x) * ri2 * gi.y + bfhi(hw[j].x) * rstdb * g.y;
;                     x.z = bflo(pw[j].y) * ri2 * gi.z + bflo(hw[j].y) * rstdb * g.z; x.w = bfhi(pw[j].y) * ri2 * gi.w + bfhi(hw[j].y) * rstdb * g.w;
;                     v2u w; w.x = pk2(x.x * rstd2 * gn.x, x.y * rstd2 * gn.y); w.y = pk2(x.z * rstd2 * gn.z, x.w * rstd2 * gn.w);
;                     *(v2u*)(pw_out + lo4 + 256 * j) = w;
;                     if (j & 1) __builtin_amdgcn_sched_barrier(0); }
	v_mul_f32_e32 v212, v196, v212
	v_mul_f32_e32 v213, v197, v213
	v_mul_f32_e32 v214, v198, v214
	v_mul_f32_e32 v215, v199, v215
	v_cvt_pk_bf16_f32 v216, v212, v213
	v_cvt_pk_bf16_f32 v217, v214, v215
	ds_read_b128 v[196:199], v71 offset:26624
	v_mul_f32_e32 v212, v70, v168
	v_mul_f32_e32 v213, v70, v169
	v_mul_f32_e32 v214, v70, v170
	v_mul_f32_e32 v215, v70, v171
	s_waitcnt lgkmcnt(1)
	v_mul_f32_e32 v212, v204, v212
	v_mul_f32_e32 v213, v205, v213
	v_mul_f32_e32 v214, v206, v214
	v_mul_f32_e32 v215, v207, v215
	v_cvt_pk_bf16_f32 v218, v212, v213
	v_cvt_pk_bf16_f32 v219, v214, v215
	s_nop 1
	v_mov_b32_dpp v220, v216 quad_perm:[1,0,3,2] row_mask:0xf bank_mask:0xf
	v_mov_b32_dpp v221, v217 quad_perm:[1,0,3,2] row_mask:0xf bank_mask:0xf
	v_mov_b32_dpp v222, v218 quad_perm:[1,0,3,2] row_mask:0xf bank_mask:0xf
	v_mov_b32_dpp v223, v219 quad_perm:[1,0,3,2] row_mask:0xf bank_mask:0xf
	v_cndmask_b32_e64 v228, v216, v222, s[92:93]
	v_cndmask_b32_e64 v229, v217, v223, s[92:93]
	v_cndmask_b32_e64 v230, v220, v218, s[92:93]
	v_cndmask_b32_e64 v231, v221, v219, s[92:93]
	global_store_dwordx4 v[226:227], v[228:231], off
	ds_read_b128 v[204:207], v71 offset:27648
	v_mul_f32_e32 v212, v70, v172
	v_mul_f32_e32 v213, v70, v173
	v_mul_f32_e32 v214, v70, v174
	v_mul_f32_e32 v215, v70, v175
	s_waitcnt lgkmcnt(1)
	v_mul_f32_e32 v212, v196, v212
	v_mul_f32_e32 v213, v197, v213
	v_mul_f32_e32 v214, v198, v214
	v_mul_f32_e32 v215, v199, v215
	v_cvt_pk_bf16_f32 v216, v212, v213
	v_cvt_pk_bf16_f32 v217, v214, v215
	ds_read_b128 v[196:199], v71 offset:28672
	v_mul_f32_e32 v212, v70, v176
	v_mul_f32_e32 v213, v70, v177
	v_mul_f32_e32 v214, v70, v178
	v_mul_f32_e32 v215, v70, v179
	s_waitcnt lgkmcnt(1)
	v_mul_f32_e32 v212, v204, v212
	v_mul_f32_e32 v213, v205, v213
	v_mul_f32_e32 v214, v206, v214
	v_mul_f32_e32 v215, v207, v215
	v_cvt_pk_bf16_f32 v218, v212, v213
	v_cvt_pk_bf16_f32 v219, v214, v215
	s_nop 1
	v_mov_b32_dpp v220, v216 quad_perm:[1,0,3,2] row_mask:0xf bank_mask:0xf
	v_mov_b32_dpp v221, v217 quad_perm:[1,0,3,2] row_mask:0xf bank_mask:0xf
	v_mov_b32_dpp v222, v218 quad_perm:[1,0,3,2] row_mask:0xf bank_mask:0xf
	v_mov_b32_dpp v223, v219 quad_perm:[1,0,3,2] row_mask:0xf bank_mask:0xf
	v_cndmask_b32_e64 v232, v216, v222, s[92:93]
	v_cndmask_b32_e64 v233, v217, v223, s[92:93]
	v_cndmask_b32_e64 v234, v220, v218, s[92:93]
	v_cndmask_b32_e64 v235, v221, v219, s[92:93]
	global_store_dwordx4 v[226:227], v[232:235], off offset:1024
	ds_read_b128 v[204:207], v71 offset:29696
	v_mul_f32_e32 v212, v70, v180
	v_mul_f32_e32 v213, v70, v181
	v_mul_f32_e32 v214, v70, v182
	v_mul_f32_e32 v215, v70, v183
	s_waitcnt lgkmcnt(1)
	v_mul_f32_e32 v212, v196, v212
	v_mul_f32_e32 v213, v197, v213
	v_mul_f32_e32 v214, v198, v214
	v_mul_f32_e32 v215, v199, v215
	v_cvt_pk_bf16_f32 v216, v212, v213
	v_cvt_pk_bf16_f32 v217, v214, v215
	ds_read_b128 v[196:199], v71 offset:30720
	v_mul_f32_e32 v212, v70, v184
	v_mul_f32_e32 v213, v70, v185
	v_mul_f32_e32 v214, v70, v186
	v_mul_f32_e32 v215, v70, v187
	s_waitcnt lgkmcnt(1)
	v_mul_f32_e32 v212, v204, v212
	v_mul_f32_e32 v213, v205, v213
	v_mul_f32_e32 v214, v206, v214
	v_mul_f32_e32 v215, v207, v215
	v_cvt_pk_bf16_f32 v218, v212, v213
	v_cvt_pk_bf16_f32 v219, v214, v215
	s_nop 1
	v_mov_b32_dpp v220, v216 quad_perm:[1,0,3,2] row_mask:0xf bank_mask:0xf
	v_mov_b32_dpp v221, v217 quad_perm:[1,0,3,2] row_mask:0xf bank_mask:0xf
	v_mov_b32_dpp v222, v218 quad_perm:[1,0,3,2] row_mask:0xf bank_mask:0xf
	v_mov_b32_dpp v223, v219 quad_perm:[1,0,3,2] row_mask:0xf bank_mask:0xf
	v_cndmask_b32_e64 v228, v216, v222, s[92:93]
	v_cndmask_b32_e64 v229, v217, v223, s[92:93]
	v_cndmask_b32_e64 v230, v220, v218, s[92:93]
	v_cndmask_b32_e64 v231, v221, v219, s[92:93]
	global_store_dwordx4 v[226:227], v[228:231], off offset:2048
	ds_read_b128 v[204:207], v71 offset:31744
	v_mul_f32_e32 v212, v70, v188
	v_mul_f32_e32 v213, v70, v189
	v_mul_f32_e32 v214, v70, v190
	v_mul_f32_e32 v215, v70, v191
	s_waitcnt lgkmcnt(1)
	v_mul_f32_e32 v212, v196, v212
	v_mul_f32_e32 v213, v197, v213
	v_mul_f32_e32 v214, v198, v214
	v_mul_f32_e32 v215, v199, v215
	v_cvt_pk_bf16_f32 v216, v212, v213
	v_cvt_pk_bf16_f32 v217, v214, v215
	v_mul_f32_e32 v212, v70, v192
	v_mul_f32_e32 v213, v70, v193
	v_mul_f32_e32 v214, v70, v194
	v_mul_f32_e32 v215, v70, v195
	s_waitcnt lgkmcnt(0)
	v_mul_f32_e32 v212, v204, v212
	v_mul_f32_e32 v213, v205, v213
	v_mul_f32_e32 v214, v206, v214
	v_mul_f32_e32 v215, v207, v215
	v_cvt_pk_bf16_f32 v218, v212, v213
	v_cvt_pk_bf16_f32 v219, v214, v215
	s_nop 1
	v_mov_b32_dpp v220, v216 quad_perm:[1,0,3,2] row_mask:0xf bank_mask:0xf
	v_mov_b32_dpp v221, v217 quad_perm:[1,0,3,2] row_mask:0xf bank_mask:0xf
	v_mov_b32_dpp v222, v218 quad_perm:[1,0,3,2] row_mask:0xf bank_mask:0xf
	v_mov_b32_dpp v223, v219 quad_perm:[1,0,3,2] row_mask:0xf bank_mask:0xf
	v_cndmask_b32_e64 v232, v216, v222, s[92:93]
	v_cndmask_b32_e64 v233, v217, v223, s[92:93]
	v_cndmask_b32_e64 v234, v220, v218, s[92:93]
	v_cndmask_b32_e64 v235, v221, v219, s[92:93]
	global_store_dwordx4 v[226:227], v[232:235], off offset:3072
	s_add_i32 s67, s67, s38
	s_add_u32 s64, s64, s8
	s_addc_u32 s65, s65, s9
	s_cmpk_lt_i32 s67, 0x2000
	v_lshl_add_u64 v[0:1], v[0:1], 0, s[10:11]
	s_cbranch_scc0 .LBB0_778

; #define LAS __attribute__((address_space(3)))
; template <int MODE> ...
;     ...
;     __syncthreads();
; #pragma unroll
;     for (int i = 0; i < 2; ++i) { const int o = 4 * (tid + NTHREADS * i);
;         if (MODE != 0) { *(LAS f32x4*)(GP + o) = *(const f32x4*)(gpost + o); const f32x4 g = *(const f32x4*)(gprev + o); *(LAS f32x4*)(GI + o) = (f32x4){1.f / g.x, 1.f / g.y, 1.f / g.z, 1.f / g.w}; }
;         if (MODE != 2) *(LAS f32x4*)(GN + o) = *(const f32x4*)(gpre + o); }
;     __syncthreads();
;     const int lo4 = 4 * lane;
; #pragma unroll 1
;     for (int row = gw; row < SEQ; row += NGW) {
.LBB0_1115:
	s_cmp_gt_i32 s36, 10
	s_cselect_b64 s[6:7], -1, 0
	s_xor_b64 s[4:5], s[4:5], -1
	s_or_b64 s[4:5], s[6:7], s[4:5]
	s_and_b64 vcc, exec, s[4:5]
	s_cbranch_vccnz .LBB0_1121
	s_mov_b64 s[12:13], 0
	s_waitcnt vmcnt(0)
	v_mbcnt_lo_u32_b32 v2, -1, 0
	v_mbcnt_hi_u32_b32 v2, -1, v2
	s_load_dwordx4 s[4:7], s[0:1], 0x70
	s_load_dwordx2 s[8:9], s[0:1], 0xa8
	v_lshlrev_b32_e32 v0, 2, v2
	v_lshl_add_u32 v24, s89, 8, v0
	v_ashrrev_i32_e32 v25, 31, v24
	v_lshlrev_b64 v[12:13], 2, v[24:25]
	v_add_u32_e32 v16, 0x800, v24
	s_waitcnt lgkmcnt(0)
	v_lshl_add_u64 v[8:9], s[4:5], 0, v[12:13]
	v_ashrrev_i32_e32 v17, 31, v16
	s_barrier
	v_lshl_add_u64 v[4:5], s[6:7], 0, v[12:13]
	global_load_dwordx4 v[8:11], v[8:9], off
	v_lshl_add_u64 v[12:13], s[8:9], 0, v[12:13]
	v_lshlrev_b64 v[26:27], 2, v[16:17]
	global_load_dwordx4 v[4:7], v[4:5], off
	v_lshl_add_u64 v[16:17], s[6:7], 0, v[26:27]
	global_load_dwordx4 v[12:15], v[12:13], off
	v_lshl_add_u64 v[20:21], s[4:5], 0, v[26:27]
	global_load_dwordx4 v[16:19], v[16:17], off
	v_lshl_add_u32 v1, v24, 2, 0
	global_load_dwordx4 v[20:23], v[20:21], off
	v_lshl_add_u64 v[24:25], s[8:9], 0, v[26:27]
	global_load_dwordx4 v[24:27], v[24:25], off
	s_cmpk_gt_i32 s40, 0x1fff
	s_waitcnt vmcnt(5)
	v_div_scale_f32 v3, s[4:5], v8, v8, 1.0
	v_div_scale_f32 v29, s[8:9], v11, v11, 1.0
	s_waitcnt vmcnt(4)
	ds_write_b128 v1, v[4:7]
	v_div_scale_f32 v5, s[4:5], v9, v9, 1.0
	s_waitcnt vmcnt(3)
	ds_write_b128 v1, v[12:15] offset:16384
	v_rcp_f32_e32 v12, v3
	v_div_scale_f32 v7, s[6:7], v10, v10, 1.0
	v_rcp_f32_e32 v13, v5
	s_waitcnt vmcnt(2)
	ds_write_b128 v1, v[16:19] offset:8192
	s_waitcnt vmcnt(1)
	v_div_scale_f32 v16, s[10:11], v20, v20, 1.0
	v_rcp_f32_e32 v14, v7
	v_rcp_f32_e32 v19, v16
	v_rcp_f32_e32 v15, v29
	v_fma_f32 v32, -v3, v12, 1.0
	v_div_scale_f32 v4, vcc, 1.0, v8, 1.0
	v_fma_f32 v33, -v5, v13, 1.0
	v_fmac_f32_e32 v12, v32, v12
	v_div_scale_f32 v6, s[4:5], 1.0, v9, 1.0
	v_fma_f32 v34, -v7, v14, 1.0
	v_fmac_f32_e32 v13, v33, v13
	v_fma_f32 v32, -v16, v19, 1.0
	v_mul_f32_e32 v33, v4, v12
	v_div_scale_f32 v28, s[6:7], 1.0, v10, 1.0
	v_fma_f32 v35, -v29, v15, 1.0
	v_fmac_f32_e32 v14, v34, v14
	v_mul_f32_e32 v34, v6, v13
	v_fmac_f32_e32 v19, v32, v19
	v_fma_f32 v32, -v3, v33, v4
	v_div_scale_f32 v30, s[8:9], 1.0, v11, 1.0
	v_fmac_f32_e32 v15, v35, v15
	v_mul_f32_e32 v35, v28, v14
	v_fma_f32 v37, -v5, v34, v6
	v_fmac_f32_e32 v33, v32, v12
	v_div_scale_f32 v17, s[10:11], 1.0, v20, 1.0
	v_mul_f32_e32 v36, v30, v15
	v_fma_f32 v38, -v7, v35, v28
	v_fmac_f32_e32 v34, v37, v13
	v_fma_f32 v3, -v3, v33, v4
	v_div_scale_f32 v18, s[14:15], v21, v21, 1.0
	v_fma_f32 v39, -v29, v36, v30
	v_mul_f32_e32 v40, v17, v19
	v_fmac_f32_e32 v35, v38, v14
	v_fma_f32 v5, -v5, v34, v6
	v_div_fmas_f32 v3, v3, v12, v33
	s_mov_b64 vcc, s[4:5]
	v_rcp_f32_e32 v31, v18
	v_fmac_f32_e32 v36, v39, v15
	v_fma_f32 v32, -v16, v40, v17
	v_fma_f32 v6, -v7, v35, v28
	v_div_fixup_f32 v4, v3, v8, 1.0
	v_div_fmas_f32 v3, v5, v13, v34
	s_mov_b64 vcc, s[6:7]
	v_fma_f32 v7, -v29, v36, v30
	v_fmac_f32_e32 v40, v32, v19
	v_div_fixup_f32 v5, v3, v9, 1.0
	v_div_fmas_f32 v3, v6, v14, v35
	s_mov_b64 vcc, s[8:9]
	v_fma_f32 v12, -v16, v40, v17
	v_div_fixup_f32 v6, v3, v10, 1.0
	v_div_fmas_f32 v3, v7, v15, v36
	s_mov_b64 vcc, s[10:11]
	v_div_fixup_f32 v7, v3, v11, 1.0
	v_div_fmas_f32 v3, v12, v19, v40
	ds_write_b128 v1, v[4:7] offset:32768
	v_div_fixup_f32 v4, v3, v20, 1.0
	v_fma_f32 v3, -v18, v31, 1.0
	v_fmac_f32_e32 v31, v3, v31
	v_div_scale_f32 v3, vcc, 1.0, v21, 1.0
	v_mul_f32_e32 v5, v3, v31
	v_fma_f32 v6, -v18, v5, v3
	v_fmac_f32_e32 v5, v6, v31
	v_div_scale_f32 v6, s[4:5], v22, v22, 1.0
	v_rcp_f32_e32 v7, v6
	v_fma_f32 v3, -v18, v5, v3
	v_div_fmas_f32 v3, v3, v31, v5
	v_div_fixup_f32 v5, v3, v21, 1.0
	v_fma_f32 v3, -v6, v7, 1.0
	v_fmac_f32_e32 v7, v3, v7
	v_div_scale_f32 v3, vcc, 1.0, v22, 1.0
	v_mul_f32_e32 v8, v3, v7
	v_fma_f32 v9, -v6, v8, v3
	v_fmac_f32_e32 v8, v9, v7
	v_div_scale_f32 v9, s[4:5], v23, v23, 1.0
	v_rcp_f32_e32 v10, v9
	v_fma_f32 v3, -v6, v8, v3
	v_div_fmas_f32 v3, v3, v7, v8
	v_div_fixup_f32 v6, v3, v22, 1.0
	v_fma_f32 v3, -v9, v10, 1.0
	v_fmac_f32_e32 v10, v3, v10
	v_div_scale_f32 v3, vcc, 1.0, v23, 1.0
	v_mul_f32_e32 v7, v3, v10
	v_fma_f32 v8, -v9, v7, v3
	v_fmac_f32_e32 v7, v8, v10
	v_fma_f32 v3, -v9, v7, v3
	v_div_fmas_f32 v3, v3, v10, v7
	v_div_fixup_f32 v7, v3, v23, 1.0
	ds_write_b128 v1, v[4:7] offset:40960
	s_waitcnt vmcnt(0)
	ds_write_b128 v1, v[24:27] offset:24576
	s_waitcnt lgkmcnt(0)
	s_barrier
	s_cbranch_scc1 .LBB0_1121
	s_load_dwordx2 s[6:7], s[0:1], 0xe8
	s_ashr_i32 s41, s40, 31
	s_lshl_b64 s[8:9], s[40:41], 2
	v_ashrrev_i32_e32 v1, 31, v0
	v_cmp_eq_u32_e64 s[4:5], 0, v2
	s_waitcnt lgkmcnt(0)
	s_add_u32 s8, s6, s8
	s_addc_u32 s9, s7, s9
	s_add_u32 s64, s8, 0x2c0000
	s_addc_u32 s65, s9, 0
	s_ashr_i32 s39, s38, 31
	s_lshl_b64 s[8:9], s[38:39], 2
	s_lshl_b64 s[10:11], s[40:41], 13
	s_add_u32 s6, s6, s10
	s_addc_u32 s7, s7, s11
	v_mbcnt_lo_u32_b32 v2, -1, 0
	v_lshl_add_u32 v71, v0, 2, 0
	v_lshl_add_u64 v[0:1], v[0:1], 1, s[6:7]
	s_lshl_b64 s[10:11], s[38:39], 13
	s_mov_b64 s[14:15], 0x3000000
	s_mov_b64 s[18:19], 0x3000200
	s_mov_b64 s[20:21], 0x3000400
	s_mov_b64 s[22:23], 0x3000600
	s_mov_b64 s[24:25], 0x3000800
	s_mov_b64 s[26:27], 0x3000a00
	s_mov_b64 s[42:43], 0x3000c00
	s_mov_b64 s[44:45], 0x3000e00
	s_mov_b64 s[46:47], 0x3001000
	s_mov_b32 s39, 0x3001000
	s_mov_b32 s41, 0x7001000
	s_mov_b64 s[48:49], 0x3001200
	s_mov_b64 s[50:51], 0x3001400
	s_mov_b64 s[52:53], 0x3001600
	s_mov_b64 s[54:55], 0x3001800
	s_mov_b64 s[56:57], 0x3001a00
	s_mov_b64 s[58:59], 0x3001c00
	s_mov_b64 s[60:61], 0x3001e00
	v_mov_b32_e32 v79, 0
	v_mov_b32_e32 v100, 0x358637bd
	s_mov_b32 s66, 0x800000
	v_mbcnt_hi_u32_b32 v101, -1, v2
	s_mov_b32 s67, s40
	s_mov_b32 s96, 0x3000000
	s_mov_b32 s97, 0x3001000
	s_mov_b32 s92, 0xaaaaaaaa
	s_mov_b32 s93, 0xaaaaaaaa
	s_branch .LBB0_1119
; #define LAS __attribute__((address_space(3)))
; __device__ __forceinline__ unsigned pk2(float lo, float hi) { const f32x2c v = {lo, hi}; return __builtin_bit_cast(unsigned, __builtin_convertvector(v, bf16x2c)); }
; __device__ __forceinline__ float bflo(unsigned w) { return __uint_as_float(w << 16); }
; __device__ __forceinline__ float bfhi(unsigned w) { return __uint_as_float(w & 0xffff0000u); }
; #define LAUNDER_ROW(pw, hw) do { LAUNDER8(pw, 0); LAUNDER8(pw, 8); LAUNDER8(hw, 0); LAUNDER8(hw, 8); } while (0)
; template <int MODE> ...
;     ...
;             if (MODE == 1) {
;                 const float rstd2 = rsqrtf(wave_sum(ss2) * (1.f / DM) + EPS);
;                 if (lane == 0) rs_out[row] = rstd2;
;                 LAUNDER_ROW(pw, hw);
;                 float ri2 = ri, rstdb = rstd; asm volatile("" : "+v"(ri2), "+v"(rstdb) :: "memory");
; #pragma unroll
;                 for (int j = 0; j < 16; ++j) { const f32x4 g = *(const LAS f32x4*)(GP + lo4 + 256 * j), gi = *(const LAS f32x4*)(GI + lo4 + 256 * j), gn = *(const LAS f32x4*)(GN + lo4 + 256 * j);
;                     f32x4 x;
;                     x.x = bflo(pw[j].x) * ri2 * gi.x + bflo(hw[j].x) * rstdb * g.x; x.y = bfhi(pw[j].x) * ri2 * gi.y + bfhi(hw[j].x) * rstdb * g.y;
;                     x.z = bflo(pw[j].y) * ri2 * gi.z + bflo(hw[j].y) * rstdb * g.z; x.w = bfhi(pw[j].y) * ri2 * gi.w + bfhi(hw[j].y) * rstdb * g.w;
;                     v2u w; w.x = pk2(x.x * rstd2 * gn.x, x.y * rstd2 * gn.y); w.y = pk2(x.z * rstd2 * gn.z, x.w * rstd2 * gn.w);
;                     *(v2u*)(pw_out + lo4 + 256 * j) = w;
;                     if (j & 1) __builtin_amdgcn_sched_barrier(0); }
.LBB0_1118:
	s_or_b64 exec, exec, s[6:7]
	v_mov_b32_e32 v78, v27
	v_mov_b32_e32 v236, 0x1f8
	v_cndmask_b32_e64 v236, 0, v236, s[92:93]
	v_add_u32_e32 v237, s96, v236
	v_add_u32_e32 v238, s97, v236
	v_add_co_u32_e32 v224, vcc, v237, v68
	s_nop 1
	v_addc_co_u32_e32 v225, vcc, 0, v69, vcc
	v_add_co_u32_e32 v226, vcc, v238, v68
	s_nop 1
	v_addc_co_u32_e32 v227, vcc, 0, v69, vcc
	ds_read_b128 v[196:199], v71 offset:16384
	ds_read_b128 v[204:207], v71 offset:17408
	v_mul_f32_e32 v212, v70, v132
	v_mul_f32_e32 v213, v70, v133
	v_mul_f32_e32 v214, v70, v134
	v_mul_f32_e32 v215, v70, v135
	s_waitcnt lgkmcnt(1)
	v_mul_f32_e32 v212, v196, v212
	v_mul_f32_e32 v213, v197, v213
	v_mul_f32_e32 v214, v198, v214
	v_mul_f32_e32 v215, v199, v215
	v_cvt_pk_bf16_f32 v216, v212, v213
	v_cvt_pk_bf16_f32 v217, v214, v215
	ds_read_b128 v[196:199], v71 offset:18432
	v_mul_f32_e32 v212, v70, v136
	v_mul_f32_e32 v213, v70, v137
	v_mul_f32_e32 v214, v70, v138
	v_mul_f32_e32 v215, v70, v139
	s_waitcnt lgkmcnt(1)
	v_mul_f32_e32 v212, v204, v212
	v_mul_f32_e32 v213, v205, v213
	v_mul_f32_e32 v214, v206, v214
	v_mul_f32_e32 v215, v207, v215
	v_cvt_pk_bf16_f32 v218, v212, v213
	v_cvt_pk_bf16_f32 v219, v214, v215
	s_nop 1
	v_mov_b32_dpp v220, v216 quad_perm:[1,0,3,2] row_mask:0xf bank_mask:0xf
	v_mov_b32_dpp v221, v217 quad_perm:[1,0,3,2] row_mask:0xf bank_mask:0xf
	v_mov_b32_dpp v222, v218 quad_perm:[1,0,3,2] row_mask:0xf bank_mask:0xf
	v_mov_b32_dpp v223, v219 quad_perm:[1,0,3,2] row_mask:0xf bank_mask:0xf
	v_cndmask_b32_e64 v228, v216, v222, s[92:93]
	v_cndmask_b32_e64 v229, v217, v223, s[92:93]
	v_cndmask_b32_e64 v230, v220, v218, s[92:93]
	v_cndmask_b32_e64 v231, v221, v219, s[92:93]
	global_store_dwordx4 v[224:225], v[228:231], off
	ds_read_b128 v[204:207], v71 offset:19456
	v_mul_f32_e32 v212, v70, v140
	v_mul_f32_e32 v213, v70, v141
	v_mul_f32_e32 v214, v70, v142
	v_mul_f32_e32 v215, v70, v143
	s_waitcnt lgkmcnt(1)
	v_mul_f32_e32 v212, v196, v212
	v_mul_f32_e32 v213, v197, v213
	v_mul_f32_e32 v214, v198, v214
	v_mul_f32_e32 v215, v199, v215
	v_cvt_pk_bf16_f32 v216, v212, v213
	v_cvt_pk_bf16_f32 v217, v214, v215
	ds_read_b128 v[196:199], v71 offset:20480
	v_mul_f32_e32 v212, v70, v144
	v_mul_f32_e32 v213, v70, v145
	v_mul_f32_e32 v214, v70, v146
	v_mul_f32_e32 v215, v70, v147
	s_waitcnt lgkmcnt(1)
	v_mul_f32_e32 v212, v204, v212
	v_mul_f32_e32 v213, v205, v213
	v_mul_f32_e32 v214, v206, v214
	v_mul_f32_e32 v215, v207, v215
	v_cvt_pk_bf16_f32 v218, v212, v213
	v_cvt_pk_bf16_f32 v219, v214, v215
	s_nop 1
	v_mov_b32_dpp v220, v216 quad_perm:[1,0,3,2] row_mask:0xf bank_mask:0xf
	v_mov_b32_dpp v221, v217 quad_perm:[1,0,3,2] row_mask:0xf bank_mask:0xf
	v_mov_b32_dpp v222, v218 quad_perm:[1,0,3,2] row_mask:0xf bank_mask:0xf
	v_mov_b32_dpp v223, v219 quad_perm:[1,0,3,2] row_mask:0xf bank_mask:0xf
	v_cndmask_b32_e64 v232, v216, v222, s[92:93]
	v_cndmask_b32_e64 v233, v217, v223, s[92:93]
	v_cndmask_b32_e64 v234, v220, v218, s[92:93]
	v_cndmask_b32_e64 v235, v221, v219, s[92:93]
	global_store_dwordx4 v[224:225], v[232:235], off offset:1024
	ds_read_b128 v[204:207], v71 offset:21504
	v_mul_f32_e32 v212, v70, v148
	v_mul_f32_e32 v213, v70, v149
	v_mul_f32_e32 v214, v70, v150
	v_mul_f32_e32 v215, v70, v151
	s_waitcnt lgkmcnt(1)
	v_mul_f32_e32 v212, v196, v212
	v_mul_f32_e32 v213, v197, v213
	v_mul_f32_e32 v214, v198, v214
	v_mul_f32_e32 v215, v199, v215
	v_cvt_pk_bf16_f32 v216, v212, v213
	v_cvt_pk_bf16_f32 v217, v214, v215
	ds_read_b128 v[196:199], v71 offset:22528
	v_mul_f32_e32 v212, v70, v152
	v_mul_f32_e32 v213, v70, v153
	v_mul_f32_e32 v214, v70, v154
	v_mul_f32_e32 v215, v70, v155
	s_waitcnt lgkmcnt(1)
	v_mul_f32_e32 v212, v204, v212
	v_mul_f32_e32 v213, v205, v213
	v_mul_f32_e32 v214, v206, v214
	v_mul_f32_e32 v215, v207, v215
	v_cvt_pk_bf16_f32 v218, v212, v213
	v_cvt_pk_bf16_f32 v219, v214, v215
	s_nop 1
	v_mov_b32_dpp v220, v216 quad_perm:[1,0,3,2] row_mask:0xf bank_mask:0xf
	v_mov_b32_dpp v221, v217 quad_perm:[1,0,3,2] row_mask:0xf bank_mask:0xf
	v_mov_b32_dpp v222, v218 quad_perm:[1,0,3,2] row_mask:0xf bank_mask:0xf
	v_mov_b32_dpp v223, v219 quad_perm:[1,0,3,2] row_mask:0xf bank_mask:0xf
	v_cndmask_b32_e64 v228, v216, v222, s[92:93]
	v_cndmask_b32_e64 v229, v217, v223, s[92:93]
	v_cndmask_b32_e64 v230, v220, v218, s[92:93]
	v_cndmask_b32_e64 v231, v221, v219, s[92:93]
	global_store_dwordx4 v[224:225], v[228:231], off offset:2048
	ds_read_b128 v[204:207], v71 offset:23552
	v_mul_f32_e32 v212, v70, v156
	v_mul_f32_e32 v213, v70, v157
	v_mul_f32_e32 v214, v70, v158
	v_mul_f32_e32 v215, v70, v159
	s_waitcnt lgkmcnt(1)
	v_mul_f32_e32 v212, v196, v212
	v_mul_f32_e32 v213, v197, v213
	v_mul_f32_e32 v214, v198, v214
	v_mul_f32_e32 v215, v199, v215
	v_cvt_pk_bf16_f32 v216, v212, v213
	v_cvt_pk_bf16_f32 v217, v214, v215
	ds_read_b128 v[196:199], v71 offset:24576
	v_mul_f32_e32 v212, v70, v160
	v_mul_f32_e32 v213, v70, v161
	v_mul_f32_e32 v214, v70, v162
	v_mul_f32_e32 v215, v70, v163
	s_waitcnt lgkmcnt(1)
	v_mul_f32_e32 v212, v204, v212
	v_mul_f32_e32 v213, v205, v213
	v_mul_f32_e32 v214, v206, v214
	v_mul_f32_e32 v215, v207, v215
	v_cvt_pk_bf16_f32 v218, v212, v213
	v_cvt_pk_bf16_f32 v219, v214, v215
	s_nop 1
	v_mov_b32_dpp v220, v216 quad_perm:[1,0,3,2] row_mask:0xf bank_mask:0xf
	v_mov_b32_dpp v221, v217 quad_perm:[1,0,3,2] row_mask:0xf bank_mask:0xf
	v_mov_b32_dpp v222, v218 quad_perm:[1,0,3,2] row_mask:0xf bank_mask:0xf
	v_mov_b32_dpp v223, v219 quad_perm:[1,0,3,2] row_mask:0xf bank_mask:0xf
	v_cndmask_b32_e64 v232, v216, v222, s[92:93]
	v_cndmask_b32_e64 v233, v217, v223, s[92:93]
	v_cndmask_b32_e64 v234, v220, v218, s[92:93]
	v_cndmask_b32_e64 v235, v221, v219, s[92:93]
	global_store_dwordx4 v[224:225], v[232:235], off offset:3072
	ds_read_b128 v[204:207], v71 offset:25600
	v_mul_f32_e32 v212, v70, v164
	v_mul_f32_e32 v213, v70, v165
	v_mul_f32_e32 v214, v70, v166
	v_mul_f32_e32 v215, v70, v167
	s_waitcnt lgkmcnt(1)
; #define LAS __attribute__((address_space(3)))
; __device__ __forceinline__ unsigned pk2(float lo, float hi) { const f32x2c v = {lo, hi}; return __builtin_bit_cast(unsigned, __builtin_convertvector(v, bf16x2c)); }
; __device__ __forceinline__ float bflo(unsigned w) { return __uint_as_float(w << 16); }
; __device__ __forceinline__ float bfhi(unsigned w) { return __uint_as_float(w & 0xffff0000u); }
; template <int MODE> ...
;     ...
;     for (int row = gw; row < SEQ; row += NGW) {
;     ...
; #pragma unroll
;                 for (int j = 0; j < 16; ++j) { const f32x4 g = *(const LAS f32x4*)(GP + lo4 + 256 * j), gi = *(const LAS f32x4*)(GI + lo4 + 256 * j), gn = *(const LAS f32x4*)(GN + lo4 + 256 * j);
;                     f32x4 x;
;                     x.x = bflo(pw[j].x) * ri2 * gi.x + bflo(hw[j].x) * rstdb * g.x; x.y = bfhi(pw[j].x) * ri2 * gi.y + bfhi(hw[j].x) * rstdb * g.y;
;                     x.z = bflo(pw[j].y) * ri2 * gi.z + bflo(hw[j].y) * rstdb * g.z; x.w = bfhi(pw[j].y) * ri2 * gi.w + bfhi(hw[j].y) * rstdb * g.w;
;                     v2u w; w.x = pk2(x.x * rstd2 * gn.x, x.y * rstd2 * gn.y); w.y = pk2(x.z * rstd2 * gn.z, x.w * rstd2 * gn.w);
;                     *(v2u*)(pw_out + lo4 + 256 * j) = w;
;                     if (j & 1) __builtin_amdgcn_sched_barrier(0); }
	v_mul_f32_e32 v212, v196, v212
	v_mul_f32_e32 v213, v197, v213
	v_mul_f32_e32 v214, v198, v214
	v_mul_f32_e32 v215, v199, v215
	v_cvt_pk_bf16_f32 v216, v212, v213
	v_cvt_pk_bf16_f32 v217, v214, v215
	ds_read_b128 v[196:199], v71 offset:26624
	v_mul_f32_e32 v212, v70, v168
	v_mul_f32_e32 v213, v70, v169
	v_mul_f32_e32 v214, v70, v170
	v_mul_f32_e32 v215, v70, v171
	s_waitcnt lgkmcnt(1)
	v_mul_f32_e32 v212, v204, v212
	v_mul_f32_e32 v213, v205, v213
	v_mul_f32_e32 v214, v206, v214
	v_mul_f32_e32 v215, v207, v215
	v_cvt_pk_bf16_f32 v218, v212, v213
	v_cvt_pk_bf16_f32 v219, v214, v215
	s_nop 1
	v_mov_b32_dpp v220, v216 quad_perm:[1,0,3,2] row_mask:0xf bank_mask:0xf
	v_mov_b32_dpp v221, v217 quad_perm:[1,0,3,2] row_mask:0xf bank_mask:0xf
	v_mov_b32_dpp v222, v218 quad_perm:[1,0,3,2] row_mask:0xf bank_mask:0xf
	v_mov_b32_dpp v223, v219 quad_perm:[1,0,3,2] row_mask:0xf bank_mask:0xf
	v_cndmask_b32_e64 v228, v216, v222, s[92:93]
	v_cndmask_b32_e64 v229, v217, v223, s[92:93]
	v_cndmask_b32_e64 v230, v220, v218, s[92:93]
	v_cndmask_b32_e64 v231, v221, v219, s[92:93]
	global_store_dwordx4 v[226:227], v[228:231], off
	ds_read_b128 v[204:207], v71 offset:27648
	v_mul_f32_e32 v212, v70, v172
	v_mul_f32_e32 v213, v70, v173
	v_mul_f32_e32 v214, v70, v174
	v_mul_f32_e32 v215, v70, v175
	s_waitcnt lgkmcnt(1)
	v_mul_f32_e32 v212, v196, v212
	v_mul_f32_e32 v213, v197, v213
	v_mul_f32_e32 v214, v198, v214
	v_mul_f32_e32 v215, v199, v215
	v_cvt_pk_bf16_f32 v216, v212, v213
	v_cvt_pk_bf16_f32 v217, v214, v215
	ds_read_b128 v[196:199], v71 offset:28672
	v_mul_f32_e32 v212, v70, v176
	v_mul_f32_e32 v213, v70, v177
	v_mul_f32_e32 v214, v70, v178
	v_mul_f32_e32 v215, v70, v179
	s_waitcnt lgkmcnt(1)
	v_mul_f32_e32 v212, v204, v212
	v_mul_f32_e32 v213, v205, v213
	v_mul_f32_e32 v214, v206, v214
	v_mul_f32_e32 v215, v207, v215
	v_cvt_pk_bf16_f32 v218, v212, v213
	v_cvt_pk_bf16_f32 v219, v214, v215
	s_nop 1
	v_mov_b32_dpp v220, v216 quad_perm:[1,0,3,2] row_mask:0xf bank_mask:0xf
	v_mov_b32_dpp v221, v217 quad_perm:[1,0,3,2] row_mask:0xf bank_mask:0xf
	v_mov_b32_dpp v222, v218 quad_perm:[1,0,3,2] row_mask:0xf bank_mask:0xf
	v_mov_b32_dpp v223, v219 quad_perm:[1,0,3,2] row_mask:0xf bank_mask:0xf
	v_cndmask_b32_e64 v232, v216, v222, s[92:93]
	v_cndmask_b32_e64 v233, v217, v223, s[92:93]
	v_cndmask_b32_e64 v234, v220, v218, s[92:93]
	v_cndmask_b32_e64 v235, v221, v219, s[92:93]
	global_store_dwordx4 v[226:227], v[232:235], off offset:1024
	ds_read_b128 v[204:207], v71 offset:29696
	v_mul_f32_e32 v212, v70, v180
	v_mul_f32_e32 v213, v70, v181
	v_mul_f32_e32 v214, v70, v182
	v_mul_f32_e32 v215, v70, v183
	s_waitcnt lgkmcnt(1)
	v_mul_f32_e32 v212, v196, v212
	v_mul_f32_e32 v213, v197, v213
	v_mul_f32_e32 v214, v198, v214
	v_mul_f32_e32 v215, v199, v215
	v_cvt_pk_bf16_f32 v216, v212, v213
	v_cvt_pk_bf16_f32 v217, v214, v215
	ds_read_b128 v[196:199], v71 offset:30720
	v_mul_f32_e32 v212, v70, v184
	v_mul_f32_e32 v213, v70, v185
	v_mul_f32_e32 v214, v70, v186
	v_mul_f32_e32 v215, v70, v187
	s_waitcnt lgkmcnt(1)
	v_mul_f32_e32 v212, v204, v212
	v_mul_f32_e32 v213, v205, v213
	v_mul_f32_e32 v214, v206, v214
	v_mul_f32_e32 v215, v207, v215
	v_cvt_pk_bf16_f32 v218, v212, v213
	v_cvt_pk_bf16_f32 v219, v214, v215
	s_nop 1
	v_mov_b32_dpp v220, v216 quad_perm:[1,0,3,2] row_mask:0xf bank_mask:0xf
	v_mov_b32_dpp v221, v217 quad_perm:[1,0,3,2] row_mask:0xf bank_mask:0xf
	v_mov_b32_dpp v222, v218 quad_perm:[1,0,3,2] row_mask:0xf bank_mask:0xf
	v_mov_b32_dpp v223, v219 quad_perm:[1,0,3,2] row_mask:0xf bank_mask:0xf
	v_cndmask_b32_e64 v228, v216, v222, s[92:93]
	v_cndmask_b32_e64 v229, v217, v223, s[92:93]
	v_cndmask_b32_e64 v230, v220, v218, s[92:93]
	v_cndmask_b32_e64 v231, v221, v219, s[92:93]
	global_store_dwordx4 v[226:227], v[228:231], off offset:2048
	ds_read_b128 v[204:207], v71 offset:31744
	v_mul_f32_e32 v212, v70, v188
	v_mul_f32_e32 v213, v70, v189
	v_mul_f32_e32 v214, v70, v190
	v_mul_f32_e32 v215, v70, v191
	s_waitcnt lgkmcnt(1)
	v_mul_f32_e32 v212, v196, v212
	v_mul_f32_e32 v213, v197, v213
	v_mul_f32_e32 v214, v198, v214
	v_mul_f32_e32 v215, v199, v215
	v_cvt_pk_bf16_f32 v216, v212, v213
	v_cvt_pk_bf16_f32 v217, v214, v215
	v_mul_f32_e32 v212, v70, v192
	v_mul_f32_e32 v213, v70, v193
	v_mul_f32_e32 v214, v70, v194
	v_mul_f32_e32 v215, v70, v195
	s_waitcnt lgkmcnt(0)
	v_mul_f32_e32 v212, v204, v212
	v_mul_f32_e32 v213, v205, v213
	v_mul_f32_e32 v214, v206, v214
	v_mul_f32_e32 v215, v207, v215
	v_cvt_pk_bf16_f32 v218, v212, v213
	v_cvt_pk_bf16_f32 v219, v214, v215
	s_nop 1
	v_mov_b32_dpp v220, v216 quad_perm:[1,0,3,2] row_mask:0xf bank_mask:0xf
	v_mov_b32_dpp v221, v217 quad_perm:[1,0,3,2] row_mask:0xf bank_mask:0xf
	v_mov_b32_dpp v222, v218 quad_perm:[1,0,3,2] row_mask:0xf bank_mask:0xf
	v_mov_b32_dpp v223, v219 quad_perm:[1,0,3,2] row_mask:0xf bank_mask:0xf
	v_cndmask_b32_e64 v232, v216, v222, s[92:93]
	v_cndmask_b32_e64 v233, v217, v223, s[92:93]
	v_cndmask_b32_e64 v234, v220, v218, s[92:93]
	v_cndmask_b32_e64 v235, v221, v219, s[92:93]
	global_store_dwordx4 v[226:227], v[232:235], off offset:3072
	s_add_i32 s67, s67, s38
	s_add_u32 s64, s64, s8
	s_addc_u32 s65, s65, s9
	s_cmpk_lt_i32 s67, 0x2000
	v_lshl_add_u64 v[0:1], v[0:1], 0, s[10:11]
	s_cbranch_scc0 .LBB0_1121

; #define LAS __attribute__((address_space(3)))
; template <int MODE> ...
;     ...
;     __syncthreads();
; #pragma unroll
;     for (int i = 0; i < 2; ++i) { const int o = 4 * (tid + NTHREADS * i);
;         if (MODE != 0) { *(LAS f32x4*)(GP + o) = *(const f32x4*)(gpost + o); const f32x4 g = *(const f32x4*)(gprev + o); *(LAS f32x4*)(GI + o) = (f32x4){1.f / g.x, 1.f / g.y, 1.f / g.z, 1.f / g.w}; }
;         if (MODE != 2) *(LAS f32x4*)(GN + o) = *(const f32x4*)(gpre + o); }
;     __syncthreads();
;     const int lo4 = 4 * lane;
; #pragma unroll 1
;     for (int row = gw; row < SEQ; row += NGW) {
.LBB0_1610:
	s_cmp_gt_i32 s36, 14
	s_cselect_b64 s[6:7], -1, 0
	s_xor_b64 s[4:5], s[4:5], -1
	s_or_b64 s[4:5], s[6:7], s[4:5]
	s_and_b64 vcc, exec, s[4:5]
	s_cbranch_vccnz .LBB0_1616
	s_mov_b64 s[12:13], 0
	s_waitcnt vmcnt(0)
	v_mbcnt_lo_u32_b32 v2, -1, 0
	v_mbcnt_hi_u32_b32 v2, -1, v2
	s_load_dwordx4 s[4:7], s[0:1], 0xa8
	s_load_dwordx2 s[8:9], s[0:1], 0x10
	v_lshlrev_b32_e32 v0, 2, v2
	v_lshl_add_u32 v24, s89, 8, v0
	v_ashrrev_i32_e32 v25, 31, v24
	v_lshlrev_b64 v[20:21], 2, v[24:25]
	v_add_u32_e32 v12, 0x800, v24
	s_waitcnt lgkmcnt(0)
	v_lshl_add_u64 v[8:9], s[4:5], 0, v[20:21]
	v_ashrrev_i32_e32 v13, 31, v12
	s_barrier
	v_lshl_add_u64 v[4:5], s[6:7], 0, v[20:21]
	global_load_dwordx4 v[8:11], v[8:9], off
	v_lshlrev_b64 v[26:27], 2, v[12:13]
	global_load_dwordx4 v[4:7], v[4:5], off
	v_lshl_add_u64 v[12:13], s[6:7], 0, v[26:27]
	v_lshl_add_u64 v[16:17], s[4:5], 0, v[26:27]
	global_load_dwordx4 v[12:15], v[12:13], off
	s_add_u32 s4, s8, 0x4000
	global_load_dwordx4 v[16:19], v[16:17], off
	s_addc_u32 s5, s9, 0
	v_lshl_add_u64 v[20:21], s[4:5], 0, v[20:21]
	global_load_dwordx4 v[20:23], v[20:21], off
	v_lshl_add_u32 v1, v24, 2, 0
	v_lshl_add_u64 v[24:25], s[4:5], 0, v[26:27]
	global_load_dwordx4 v[24:27], v[24:25], off
	s_cmpk_gt_i32 s40, 0x1fff
	s_waitcnt vmcnt(5)
	v_div_scale_f32 v3, s[4:5], v8, v8, 1.0
	s_waitcnt vmcnt(4)
	ds_write_b128 v1, v[4:7]
	v_div_scale_f32 v5, s[4:5], v9, v9, 1.0
	v_rcp_f32_e32 v31, v3
	v_div_scale_f32 v7, s[6:7], v10, v10, 1.0
	v_rcp_f32_e32 v32, v5
	s_waitcnt vmcnt(3)
	ds_write_b128 v1, v[12:15] offset:8192
	s_waitcnt vmcnt(2)
	v_div_scale_f32 v12, s[10:11], v16, v16, 1.0
	v_div_scale_f32 v29, s[8:9], v11, v11, 1.0
	v_rcp_f32_e32 v33, v7
	v_rcp_f32_e32 v15, v12
	v_rcp_f32_e32 v34, v29
	s_waitcnt vmcnt(1)
	ds_write_b128 v1, v[20:23] offset:16384
	v_fma_f32 v21, -v3, v31, 1.0
	v_div_scale_f32 v4, vcc, 1.0, v8, 1.0
	v_fma_f32 v22, -v5, v32, 1.0
	v_fmac_f32_e32 v31, v21, v31
	v_div_scale_f32 v6, s[4:5], 1.0, v9, 1.0
	v_fma_f32 v23, -v7, v33, 1.0
	v_fmac_f32_e32 v32, v22, v32
	v_fma_f32 v21, -v12, v15, 1.0
	v_mul_f32_e32 v22, v4, v31
	v_div_scale_f32 v28, s[6:7], 1.0, v10, 1.0
	v_fma_f32 v35, -v29, v34, 1.0
	v_fmac_f32_e32 v33, v23, v33
	v_mul_f32_e32 v23, v6, v32
	v_fmac_f32_e32 v15, v21, v15
	v_fma_f32 v21, -v3, v22, v4
	v_div_scale_f32 v30, s[8:9], 1.0, v11, 1.0
	v_fmac_f32_e32 v34, v35, v34
	v_mul_f32_e32 v35, v28, v33
	v_fma_f32 v37, -v5, v23, v6
	v_fmac_f32_e32 v22, v21, v31
	v_div_scale_f32 v13, s[10:11], 1.0, v16, 1.0
	v_mul_f32_e32 v36, v30, v34
	v_fma_f32 v38, -v7, v35, v28
	v_fmac_f32_e32 v23, v37, v32
	v_fma_f32 v3, -v3, v22, v4
	v_div_scale_f32 v14, s[14:15], v17, v17, 1.0
	v_fma_f32 v39, -v29, v36, v30
	v_mul_f32_e32 v40, v13, v15
	v_fmac_f32_e32 v35, v38, v33
	v_fma_f32 v5, -v5, v23, v6
	v_div_fmas_f32 v3, v3, v31, v22
	s_mov_b64 vcc, s[4:5]
	v_rcp_f32_e32 v20, v14
	v_fmac_f32_e32 v36, v39, v34
	v_fma_f32 v21, -v12, v40, v13
	v_fma_f32 v6, -v7, v35, v28
	v_div_fixup_f32 v4, v3, v8, 1.0
	v_div_fmas_f32 v3, v5, v32, v23
	s_mov_b64 vcc, s[6:7]
	v_fma_f32 v7, -v29, v36, v30
	v_fmac_f32_e32 v40, v21, v15
	v_div_fixup_f32 v5, v3, v9, 1.0
	v_div_fmas_f32 v3, v6, v33, v35
	s_mov_b64 vcc, s[8:9]
	v_fma_f32 v12, -v12, v40, v13
	v_div_fixup_f32 v6, v3, v10, 1.0
	v_div_fmas_f32 v3, v7, v34, v36
	s_mov_b64 vcc, s[10:11]
	v_div_fixup_f32 v7, v3, v11, 1.0
	v_div_fmas_f32 v3, v12, v15, v40
	ds_write_b128 v1, v[4:7] offset:32768
	v_div_fixup_f32 v4, v3, v16, 1.0
	v_fma_f32 v3, -v14, v20, 1.0
	v_fmac_f32_e32 v20, v3, v20
	v_div_scale_f32 v3, vcc, 1.0, v17, 1.0
	v_mul_f32_e32 v5, v3, v20
	v_fma_f32 v6, -v14, v5, v3
	v_fmac_f32_e32 v5, v6, v20
	v_div_scale_f32 v6, s[4:5], v18, v18, 1.0
	v_rcp_f32_e32 v7, v6
	v_fma_f32 v3, -v14, v5, v3
	v_div_fmas_f32 v3, v3, v20, v5
	v_div_fixup_f32 v5, v3, v17, 1.0
	v_fma_f32 v3, -v6, v7, 1.0
	v_fmac_f32_e32 v7, v3, v7
	v_div_scale_f32 v3, vcc, 1.0, v18, 1.0
	v_mul_f32_e32 v8, v3, v7
	v_fma_f32 v9, -v6, v8, v3
	v_fmac_f32_e32 v8, v9, v7
	v_div_scale_f32 v9, s[4:5], v19, v19, 1.0
	v_rcp_f32_e32 v10, v9
	v_fma_f32 v3, -v6, v8, v3
	v_div_fmas_f32 v3, v3, v7, v8
	v_div_fixup_f32 v6, v3, v18, 1.0
	v_fma_f32 v3, -v9, v10, 1.0
	v_fmac_f32_e32 v10, v3, v10
	v_div_scale_f32 v3, vcc, 1.0, v19, 1.0
	v_mul_f32_e32 v7, v3, v10
	v_fma_f32 v8, -v9, v7, v3
	v_fmac_f32_e32 v7, v8, v10
	v_fma_f32 v3, -v9, v7, v3
	v_div_fmas_f32 v3, v3, v10, v7
	v_div_fixup_f32 v7, v3, v19, 1.0
	ds_write_b128 v1, v[4:7] offset:40960
	s_waitcnt vmcnt(0)
	ds_write_b128 v1, v[24:27] offset:24576
	s_waitcnt lgkmcnt(0)
	s_barrier
	s_cbranch_scc1 .LBB0_1616
	s_load_dwordx2 s[6:7], s[0:1], 0xe8
	s_ashr_i32 s41, s40, 31
	s_lshl_b64 s[8:9], s[40:41], 2
	v_ashrrev_i32_e32 v1, 31, v0
	v_cmp_eq_u32_e64 s[4:5], 0, v2
	s_waitcnt lgkmcnt(0)
	s_add_u32 s8, s6, s8
	s_addc_u32 s9, s7, s9
	s_add_u32 s64, s8, 0x2c0000
	s_addc_u32 s65, s9, 0
	s_ashr_i32 s39, s38, 31
	s_lshl_b64 s[8:9], s[38:39], 2
	s_lshl_b64 s[10:11], s[40:41], 13
	s_add_u32 s6, s6, s10
	s_addc_u32 s7, s7, s11
	v_mbcnt_lo_u32_b32 v2, -1, 0
	v_lshl_add_u32 v71, v0, 2, 0
	v_lshl_add_u64 v[0:1], v[0:1], 1, s[6:7]
	s_lshl_b64 s[10:11], s[38:39], 13
	s_mov_b64 s[14:15], 0x3000000
	s_mov_b64 s[18:19], 0x3000200
	s_mov_b64 s[20:21], 0x3000400
	s_mov_b64 s[22:23], 0x3000600
	s_mov_b64 s[24:25], 0x3000800
	s_mov_b64 s[26:27], 0x3000a00
	s_mov_b64 s[42:43], 0x3000c00
	s_mov_b64 s[44:45], 0x3000e00
	s_mov_b64 s[46:47], 0x3001000
	s_mov_b32 s39, 0x3001000
	s_mov_b32 s41, 0x7001000
	s_mov_b64 s[48:49], 0x3001200
	s_mov_b64 s[50:51], 0x3001400
	s_mov_b64 s[52:53], 0x3001600
	s_mov_b64 s[54:55], 0x3001800
	s_mov_b64 s[56:57], 0x3001a00
	s_mov_b64 s[58:59], 0x3001c00
	s_mov_b64 s[60:61], 0x3001e00
	v_mov_b32_e32 v98, 0
	v_mov_b32_e32 v99, 0x358637bd
	s_mov_b32 s66, 0x800000
	v_mbcnt_hi_u32_b32 v100, -1, v2
	s_mov_b32 s67, s40
	s_mov_b32 s96, 0x3000000
	s_mov_b32 s97, 0x3001000
	s_mov_b32 s92, 0xaaaaaaaa
	s_mov_b32 s93, 0xaaaaaaaa
	s_branch .LBB0_1614

; #define LAS __attribute__((address_space(3)))
; template <int MODE> ...
;     ...
;     __syncthreads();
; #pragma unroll
;     for (int i = 0; i < 2; ++i) { const int o = 4 * (tid + NTHREADS * i);
;         if (MODE != 0) { *(LAS f32x4*)(GP + o) = *(const f32x4*)(gpost + o); const f32x4 g = *(const f32x4*)(gprev + o); *(LAS f32x4*)(GI + o) = (f32x4){1.f / g.x, 1.f / g.y, 1.f / g.z, 1.f / g.w}; }
;         if (MODE != 2) *(LAS f32x4*)(GN + o) = *(const f32x4*)(gpre + o); }
;     __syncthreads();
;     const int lo4 = 4 * lane;
; #pragma unroll 1
;     for (int row = gw; row < SEQ; row += NGW) {
.LBB0_1984:
	s_cmp_gt_i32 s36, 18
	s_cselect_b64 s[6:7], -1, 0
	s_xor_b64 s[4:5], s[4:5], -1
	s_or_b64 s[4:5], s[6:7], s[4:5]
	s_and_b64 vcc, exec, s[4:5]
	s_cbranch_vccnz .LBB0_1990
	s_mov_b64 s[12:13], 0
	s_waitcnt vmcnt(0)
	v_mbcnt_lo_u32_b32 v2, -1, 0
	v_mbcnt_hi_u32_b32 v2, -1, v2
	s_load_dwordx4 s[4:7], s[0:1], 0x10
	s_load_dwordx2 s[8:9], s[0:1], 0x70
	v_lshlrev_b32_e32 v0, 2, v2
	v_lshl_add_u32 v24, s89, 8, v0
	v_ashrrev_i32_e32 v25, 31, v24
	s_waitcnt lgkmcnt(0)
	s_add_u32 s4, s4, 0x4000
	s_addc_u32 s5, s5, 0
	v_lshlrev_b64 v[20:21], 2, v[24:25]
	v_lshl_add_u64 v[4:5], s[4:5], 0, v[20:21]
	v_add_u32_e32 v8, 0x800, v24
	s_barrier
	global_load_dwordx4 v[4:7], v[4:5], off
	v_ashrrev_i32_e32 v9, 31, v8
	v_lshlrev_b64 v[26:27], 2, v[8:9]
	v_lshl_add_u64 v[8:9], s[4:5], 0, v[26:27]
	s_add_u32 s4, s6, 0x4000
	s_addc_u32 s5, s7, 0
	s_add_u32 s6, s8, 0x4000
	v_lshl_add_u64 v[22:23], s[4:5], 0, v[20:21]
	global_load_dwordx4 v[8:11], v[8:9], off
	v_lshl_add_u64 v[28:29], s[4:5], 0, v[26:27]
	s_addc_u32 s7, s9, 0
	global_load_dwordx4 v[12:15], v[22:23], off
	global_load_dwordx4 v[16:19], v[28:29], off
	v_lshl_add_u64 v[20:21], s[6:7], 0, v[20:21]
	global_load_dwordx4 v[20:23], v[20:21], off
	v_lshl_add_u32 v1, v24, 2, 0
	v_lshl_add_u64 v[24:25], s[6:7], 0, v[26:27]
	global_load_dwordx4 v[24:27], v[24:25], off
	s_cmpk_gt_i32 s40, 0x1fff
	s_waitcnt vmcnt(3)
	ds_write_b128 v1, v[12:15]
	s_waitcnt vmcnt(2)
	ds_write_b128 v1, v[16:19] offset:8192
	s_waitcnt vmcnt(1)
	ds_write_b128 v1, v[20:23] offset:16384
	v_div_scale_f32 v3, s[4:5], v4, v4, 1.0
	v_div_scale_f32 v29, s[4:5], v5, v5, 1.0
	v_rcp_f32_e32 v37, v3
	v_div_scale_f32 v31, s[6:7], v6, v6, 1.0
	v_rcp_f32_e32 v38, v29
	v_div_scale_f32 v33, s[8:9], v7, v7, 1.0
	v_rcp_f32_e32 v39, v31
	v_rcp_f32_e32 v40, v33
	v_fma_f32 v12, -v3, v37, 1.0
	v_div_scale_f32 v28, vcc, 1.0, v4, 1.0
	v_fma_f32 v13, -v29, v38, 1.0
	v_fmac_f32_e32 v37, v12, v37
	v_div_scale_f32 v30, s[4:5], 1.0, v5, 1.0
	v_fma_f32 v14, -v31, v39, 1.0
	v_fmac_f32_e32 v38, v13, v38
	v_mul_f32_e32 v12, v28, v37
	v_div_scale_f32 v32, s[6:7], 1.0, v6, 1.0
	v_fma_f32 v15, -v33, v40, 1.0
	v_fmac_f32_e32 v39, v14, v39
	v_mul_f32_e32 v13, v30, v38
	v_fma_f32 v17, -v3, v12, v28
	v_div_scale_f32 v34, s[8:9], 1.0, v7, 1.0
	v_fmac_f32_e32 v40, v15, v40
	v_mul_f32_e32 v14, v32, v39
	v_fma_f32 v18, -v29, v13, v30
	v_fmac_f32_e32 v12, v17, v37
	v_div_scale_f32 v35, s[10:11], v8, v8, 1.0
	v_mul_f32_e32 v15, v34, v40
	v_fma_f32 v19, -v31, v14, v32
	v_fmac_f32_e32 v13, v18, v38
	v_fma_f32 v3, -v3, v12, v28
	v_rcp_f32_e32 v41, v35
	v_fma_f32 v20, -v33, v15, v34
	v_fmac_f32_e32 v14, v19, v39
	v_fma_f32 v17, -v29, v13, v30
	v_div_fmas_f32 v3, v3, v37, v12
	s_mov_b64 vcc, s[4:5]
	v_fmac_f32_e32 v15, v20, v40
	v_fma_f32 v18, -v31, v14, v32
	v_div_fixup_f32 v4, v3, v4, 1.0
	v_div_fmas_f32 v3, v17, v38, v13
	s_mov_b64 vcc, s[6:7]
	v_fma_f32 v19, -v33, v15, v34
	v_div_fixup_f32 v5, v3, v5, 1.0
	v_div_fmas_f32 v3, v18, v39, v14
	s_mov_b64 vcc, s[8:9]
	v_div_fixup_f32 v6, v3, v6, 1.0
	v_div_fmas_f32 v3, v19, v40, v15
	v_fma_f32 v16, -v35, v41, 1.0
	v_div_fixup_f32 v7, v3, v7, 1.0
	v_div_scale_f32 v3, s[4:5], v9, v9, 1.0
	v_div_scale_f32 v36, s[10:11], 1.0, v8, 1.0
	v_fmac_f32_e32 v41, v16, v41
	ds_write_b128 v1, v[4:7] offset:32768
	v_rcp_f32_e32 v5, v3
	v_mul_f32_e32 v16, v36, v41
	v_fma_f32 v21, -v35, v16, v36
	v_fmac_f32_e32 v16, v21, v41
	v_fma_f32 v20, -v35, v16, v36
	s_mov_b64 vcc, s[10:11]
	v_fma_f32 v6, -v3, v5, 1.0
	v_div_fmas_f32 v4, v20, v41, v16
	v_fmac_f32_e32 v5, v6, v5
	v_div_scale_f32 v6, vcc, 1.0, v9, 1.0
	v_mul_f32_e32 v7, v6, v5
	v_div_fixup_f32 v4, v4, v8, 1.0
	v_fma_f32 v8, -v3, v7, v6
	v_fmac_f32_e32 v7, v8, v5
	v_fma_f32 v3, -v3, v7, v6
	v_div_scale_f32 v6, s[4:5], v10, v10, 1.0
	v_rcp_f32_e32 v8, v6
	v_div_fmas_f32 v3, v3, v5, v7
	v_div_fixup_f32 v5, v3, v9, 1.0
	v_fma_f32 v3, -v6, v8, 1.0
	v_fmac_f32_e32 v8, v3, v8
	v_div_scale_f32 v3, vcc, 1.0, v10, 1.0
	v_mul_f32_e32 v7, v3, v8
	v_fma_f32 v9, -v6, v7, v3
	v_fmac_f32_e32 v7, v9, v8
	v_div_scale_f32 v9, s[4:5], v11, v11, 1.0
	v_rcp_f32_e32 v12, v9
	v_fma_f32 v3, -v6, v7, v3
	v_div_fmas_f32 v3, v3, v8, v7
	v_div_fixup_f32 v6, v3, v10, 1.0
	v_fma_f32 v3, -v9, v12, 1.0
	v_fmac_f32_e32 v12, v3, v12
	v_div_scale_f32 v3, vcc, 1.0, v11, 1.0
	v_mul_f32_e32 v7, v3, v12
	v_fma_f32 v8, -v9, v7, v3
	v_fmac_f32_e32 v7, v8, v12
	v_fma_f32 v3, -v9, v7, v3
	v_div_fmas_f32 v3, v3, v12, v7
	v_div_fixup_f32 v7, v3, v11, 1.0
	ds_write_b128 v1, v[4:7] offset:40960
	s_waitcnt vmcnt(0)
	ds_write_b128 v1, v[24:27] offset:24576
	s_waitcnt lgkmcnt(0)
	s_barrier
	s_cbranch_scc1 .LBB0_1990
	s_load_dwordx2 s[6:7], s[0:1], 0xe8
	s_ashr_i32 s41, s40, 31
	s_lshl_b64 s[8:9], s[40:41], 2
	v_ashrrev_i32_e32 v1, 31, v0
	v_cmp_eq_u32_e64 s[4:5], 0, v2
	s_waitcnt lgkmcnt(0)
	s_add_u32 s8, s6, s8
	s_addc_u32 s9, s7, s9
	s_add_u32 s64, s8, 0x2c0000
	s_addc_u32 s65, s9, 0
	s_ashr_i32 s39, s38, 31
	s_lshl_b64 s[8:9], s[38:39], 2
	s_lshl_b64 s[10:11], s[40:41], 13
	s_add_u32 s6, s6, s10
	s_addc_u32 s7, s7, s11
	v_mbcnt_lo_u32_b32 v2, -1, 0
	v_lshl_add_u32 v71, v0, 2, 0
	v_lshl_add_u64 v[0:1], v[0:1], 1, s[6:7]
	s_lshl_b64 s[10:11], s[38:39], 13
	s_mov_b64 s[14:15], 0x3000000
	s_mov_b64 s[18:19], 0x3000200
	s_mov_b64 s[20:21], 0x3000400
	s_mov_b64 s[22:23], 0x3000600
	s_mov_b64 s[24:25], 0x3000800
	s_mov_b64 s[26:27], 0x3000a00
	s_mov_b64 s[42:43], 0x3000c00
	s_mov_b64 s[44:45], 0x3000e00
	s_mov_b64 s[46:47], 0x3001000
	s_mov_b32 s39, 0x3001000
	s_mov_b32 s41, 0x7001000
	s_mov_b64 s[48:49], 0x3001200
	s_mov_b64 s[50:51], 0x3001400
	s_mov_b64 s[52:53], 0x3001600
	s_mov_b64 s[54:55], 0x3001800
	s_mov_b64 s[56:57], 0x3001a00
	s_mov_b64 s[58:59], 0x3001c00
	s_mov_b64 s[60:61], 0x3001e00
	v_mov_b32_e32 v79, 0
	v_mov_b32_e32 v100, 0x358637bd
	s_mov_b32 s66, 0x800000
	v_mbcnt_hi_u32_b32 v101, -1, v2
	s_mov_b32 s67, s40
	s_mov_b32 s96, 0x3000000
	s_mov_b32 s97, 0x3001000
	s_mov_b32 s92, 0xaaaaaaaa
	s_mov_b32 s93, 0xaaaaaaaa
	s_branch .LBB0_1988

; #define LAS __attribute__((address_space(3)))
; template <int MODE> ...
;     ...
;     __syncthreads();
; #pragma unroll
;     for (int i = 0; i < 2; ++i) { const int o = 4 * (tid + NTHREADS * i);
;         if (MODE != 0) { *(LAS f32x4*)(GP + o) = *(const f32x4*)(gpost + o); const f32x4 g = *(const f32x4*)(gprev + o); *(LAS f32x4*)(GI + o) = (f32x4){1.f / g.x, 1.f / g.y, 1.f / g.z, 1.f / g.w}; }
;         if (MODE != 2) *(LAS f32x4*)(GN + o) = *(const f32x4*)(gpre + o); }
;     __syncthreads();
;     const int lo4 = 4 * lane;
; #pragma unroll 1
;     for (int row = gw; row < SEQ; row += NGW) {
.LBB0_2327:
	s_cmp_gt_i32 s36, 22
	s_cselect_b64 s[6:7], -1, 0
	s_xor_b64 s[4:5], s[4:5], -1
	s_or_b64 s[4:5], s[6:7], s[4:5]
	s_and_b64 vcc, exec, s[4:5]
	s_cbranch_vccnz .LBB0_2333
	s_mov_b64 s[12:13], 0
	s_waitcnt vmcnt(0)
	v_mbcnt_lo_u32_b32 v2, -1, 0
	v_mbcnt_hi_u32_b32 v2, -1, v2
	s_load_dwordx4 s[4:7], s[0:1], 0x70
	s_load_dwordx2 s[8:9], s[0:1], 0xa8
	v_lshlrev_b32_e32 v0, 2, v2
	v_lshl_add_u32 v24, s89, 8, v0
	v_ashrrev_i32_e32 v25, 31, v24
	s_waitcnt lgkmcnt(0)
	s_add_u32 s4, s4, 0x4000
	s_addc_u32 s5, s5, 0
	v_lshlrev_b64 v[20:21], 2, v[24:25]
	v_lshl_add_u64 v[4:5], s[4:5], 0, v[20:21]
	v_add_u32_e32 v8, 0x800, v24
	s_barrier
	global_load_dwordx4 v[4:7], v[4:5], off
	v_ashrrev_i32_e32 v9, 31, v8
	v_lshlrev_b64 v[26:27], 2, v[8:9]
	v_lshl_add_u64 v[8:9], s[4:5], 0, v[26:27]
	s_add_u32 s4, s6, 0x4000
	s_addc_u32 s5, s7, 0
	s_add_u32 s6, s8, 0x4000
	v_lshl_add_u64 v[22:23], s[4:5], 0, v[20:21]
	global_load_dwordx4 v[8:11], v[8:9], off
	v_lshl_add_u64 v[28:29], s[4:5], 0, v[26:27]
	s_addc_u32 s7, s9, 0
	global_load_dwordx4 v[12:15], v[22:23], off
	global_load_dwordx4 v[16:19], v[28:29], off
	v_lshl_add_u64 v[20:21], s[6:7], 0, v[20:21]
	global_load_dwordx4 v[20:23], v[20:21], off
	v_lshl_add_u32 v1, v24, 2, 0
	v_lshl_add_u64 v[24:25], s[6:7], 0, v[26:27]
	global_load_dwordx4 v[24:27], v[24:25], off
	s_cmpk_gt_i32 s40, 0x1fff
	s_waitcnt vmcnt(3)
	ds_write_b128 v1, v[12:15]
	s_waitcnt vmcnt(2)
	ds_write_b128 v1, v[16:19] offset:8192
	s_waitcnt vmcnt(1)
	ds_write_b128 v1, v[20:23] offset:16384
	v_div_scale_f32 v3, s[4:5], v4, v4, 1.0
	v_div_scale_f32 v29, s[4:5], v5, v5, 1.0
	v_rcp_f32_e32 v37, v3
	v_div_scale_f32 v31, s[6:7], v6, v6, 1.0
	v_rcp_f32_e32 v38, v29
	v_div_scale_f32 v33, s[8:9], v7, v7, 1.0
	v_rcp_f32_e32 v39, v31
	v_rcp_f32_e32 v40, v33
	v_fma_f32 v12, -v3, v37, 1.0
	v_div_scale_f32 v28, vcc, 1.0, v4, 1.0
	v_fma_f32 v13, -v29, v38, 1.0
	v_fmac_f32_e32 v37, v12, v37
	v_div_scale_f32 v30, s[4:5], 1.0, v5, 1.0
	v_fma_f32 v14, -v31, v39, 1.0
	v_fmac_f32_e32 v38, v13, v38
	v_mul_f32_e32 v12, v28, v37
	v_div_scale_f32 v32, s[6:7], 1.0, v6, 1.0
	v_fma_f32 v15, -v33, v40, 1.0
	v_fmac_f32_e32 v39, v14, v39
	v_mul_f32_e32 v13, v30, v38
	v_fma_f32 v17, -v3, v12, v28
	v_div_scale_f32 v34, s[8:9], 1.0, v7, 1.0
	v_fmac_f32_e32 v40, v15, v40
	v_mul_f32_e32 v14, v32, v39
	v_fma_f32 v18, -v29, v13, v30
	v_fmac_f32_e32 v12, v17, v37
	v_div_scale_f32 v35, s[10:11], v8, v8, 1.0
	v_mul_f32_e32 v15, v34, v40
	v_fma_f32 v19, -v31, v14, v32
	v_fmac_f32_e32 v13, v18, v38
	v_fma_f32 v3, -v3, v12, v28
	v_rcp_f32_e32 v41, v35
	v_fma_f32 v20, -v33, v15, v34
	v_fmac_f32_e32 v14, v19, v39
	v_fma_f32 v17, -v29, v13, v30
	v_div_fmas_f32 v3, v3, v37, v12
	s_mov_b64 vcc, s[4:5]
	v_fmac_f32_e32 v15, v20, v40
	v_fma_f32 v18, -v31, v14, v32
	v_div_fixup_f32 v4, v3, v4, 1.0
	v_div_fmas_f32 v3, v17, v38, v13
	s_mov_b64 vcc, s[6:7]
	v_fma_f32 v19, -v33, v15, v34
	v_div_fixup_f32 v5, v3, v5, 1.0
	v_div_fmas_f32 v3, v18, v39, v14
	s_mov_b64 vcc, s[8:9]
	v_div_fixup_f32 v6, v3, v6, 1.0
	v_div_fmas_f32 v3, v19, v40, v15
	v_fma_f32 v16, -v35, v41, 1.0
	v_div_fixup_f32 v7, v3, v7, 1.0
	v_div_scale_f32 v3, s[4:5], v9, v9, 1.0
	v_div_scale_f32 v36, s[10:11], 1.0, v8, 1.0
	v_fmac_f32_e32 v41, v16, v41
	ds_write_b128 v1, v[4:7] offset:32768
	v_rcp_f32_e32 v5, v3
	v_mul_f32_e32 v16, v36, v41
	v_fma_f32 v21, -v35, v16, v36
	v_fmac_f32_e32 v16, v21, v41
	v_fma_f32 v20, -v35, v16, v36
	s_mov_b64 vcc, s[10:11]
	v_fma_f32 v6, -v3, v5, 1.0
	v_div_fmas_f32 v4, v20, v41, v16
	v_fmac_f32_e32 v5, v6, v5
	v_div_scale_f32 v6, vcc, 1.0, v9, 1.0
	v_mul_f32_e32 v7, v6, v5
	v_div_fixup_f32 v4, v4, v8, 1.0
	v_fma_f32 v8, -v3, v7, v6
	v_fmac_f32_e32 v7, v8, v5
	v_fma_f32 v3, -v3, v7, v6
	v_div_scale_f32 v6, s[4:5], v10, v10, 1.0
	v_rcp_f32_e32 v8, v6
	v_div_fmas_f32 v3, v3, v5, v7
	v_div_fixup_f32 v5, v3, v9, 1.0
	v_fma_f32 v3, -v6, v8, 1.0
	v_fmac_f32_e32 v8, v3, v8
	v_div_scale_f32 v3, vcc, 1.0, v10, 1.0
	v_mul_f32_e32 v7, v3, v8
	v_fma_f32 v9, -v6, v7, v3
	v_fmac_f32_e32 v7, v9, v8
	v_div_scale_f32 v9, s[4:5], v11, v11, 1.0
	v_rcp_f32_e32 v12, v9
	v_fma_f32 v3, -v6, v7, v3
	v_div_fmas_f32 v3, v3, v8, v7
	v_div_fixup_f32 v6, v3, v10, 1.0
	v_fma_f32 v3, -v9, v12, 1.0
	v_fmac_f32_e32 v12, v3, v12
	v_div_scale_f32 v3, vcc, 1.0, v11, 1.0
	v_mul_f32_e32 v7, v3, v12
	v_fma_f32 v8, -v9, v7, v3
	v_fmac_f32_e32 v7, v8, v12
	v_fma_f32 v3, -v9, v7, v3
	v_div_fmas_f32 v3, v3, v12, v7
	v_div_fixup_f32 v7, v3, v11, 1.0
	ds_write_b128 v1, v[4:7] offset:40960
	s_waitcnt vmcnt(0)
	ds_write_b128 v1, v[24:27] offset:24576
	s_waitcnt lgkmcnt(0)
	s_barrier
	s_cbranch_scc1 .LBB0_2333
	s_load_dwordx2 s[6:7], s[0:1], 0xe8
	s_ashr_i32 s41, s40, 31
	s_lshl_b64 s[8:9], s[40:41], 2
	v_ashrrev_i32_e32 v1, 31, v0
	v_cmp_eq_u32_e64 s[4:5], 0, v2
	s_waitcnt lgkmcnt(0)
	s_add_u32 s8, s6, s8
	s_addc_u32 s9, s7, s9
	s_add_u32 s64, s8, 0x2c0000
	s_addc_u32 s65, s9, 0
	s_ashr_i32 s39, s38, 31
	s_lshl_b64 s[8:9], s[38:39], 2
	s_lshl_b64 s[10:11], s[40:41], 13
	s_add_u32 s6, s6, s10
	s_addc_u32 s7, s7, s11
	v_mbcnt_lo_u32_b32 v2, -1, 0
	v_lshl_add_u32 v71, v0, 2, 0
	v_lshl_add_u64 v[0:1], v[0:1], 1, s[6:7]
	s_lshl_b64 s[10:11], s[38:39], 13
	s_mov_b64 s[14:15], 0x3000000
	s_mov_b64 s[18:19], 0x3000200
	s_mov_b64 s[20:21], 0x3000400
	s_mov_b64 s[22:23], 0x3000600
	s_mov_b64 s[24:25], 0x3000800
	s_mov_b64 s[26:27], 0x3000a00
	s_mov_b64 s[42:43], 0x3000c00
	s_mov_b64 s[44:45], 0x3000e00
	s_mov_b64 s[46:47], 0x3001000
	s_mov_b32 s39, 0x3001000
	s_mov_b32 s41, 0x7001000
	s_mov_b64 s[48:49], 0x3001200
	s_mov_b64 s[50:51], 0x3001400
	s_mov_b64 s[52:53], 0x3001600
	s_mov_b64 s[54:55], 0x3001800
	s_mov_b64 s[56:57], 0x3001a00
	s_mov_b64 s[58:59], 0x3001c00
	s_mov_b64 s[60:61], 0x3001e00
	v_mov_b32_e32 v98, 0
	v_mov_b32_e32 v99, 0x358637bd
	s_mov_b32 s66, 0x800000
	v_mbcnt_hi_u32_b32 v100, -1, v2
	s_mov_b32 s67, s40
	s_mov_b32 s96, 0x3000000
	s_mov_b32 s97, 0x3001000
	s_mov_b32 s92, 0xaaaaaaaa
	s_mov_b32 s93, 0xaaaaaaaa
	s_branch .LBB0_2331
